# v26: v25 + 16B merged bf16 stores for part of the in-projection epilogue
# baseline (speedup 1.0000x reference)
; __device__ __forceinline__ unsigned pk2(float lo, float hi) { f32x2_t v = {lo, hi}; bf16x2_t b = __builtin_convertvector(v, bf16x2_t); return __builtin_bit_cast(unsigned, b); }
;     __device__ __forceinline__ void operator()(const f32x4 (&acc)[2][2][4][2], const Unit& u, int wr, int wc, int fr, int fq) const {
;     ...
;         } else if (wc == 0) {
; #pragma unroll
;             for (int ai = 0; ai < 2; ++ai)
; #pragma unroll
;                 for (int m = 0; m < 4; ++m) { const int row = row0 + ai * HALF + m * 16; const float* rp = rope + posidx(row) * 32 + 4 * fq;
;                     const f32x4 v0 = acc[ai][0][m][0], v1 = acc[ai][0][m][1], c = *(const f32x4*)rp, s = *(const f32x4*)(rp + 16); const f32x4 o0 = v0 * c - v1 * s, o1 = v1 * c + v0 * s;
;                     float* ko = out + (row < NPR ? O_KRP + (size_t)row * 32 : O_KRS + (size_t)(row - NPR) * 32) + 4 * fq; *(f32x4*)ko = o0; *(f32x4*)(ko + 16) = o1;
;                     u32x2 w0, w1; w0.x = pk2(o0[0], o0[1]); w0.y = pk2(o0[2], o0[3]); w1.x = pk2(o1[0], o1[1]); w1.y = pk2(o1[2], o1[3]);
;                     *(u32x2*)(KRB + (size_t)row * 32 + 4 * fq) = w0; *(u32x2*)(KRB + (size_t)row * 32 + 16 + 4 * fq) = w1; }
.LBB0_239:
	s_lshl_b32 s26, s6, 8
	v_mbcnt_lo_u32_b32 v182, -1, 0
	v_mbcnt_hi_u32_b32 v182, -1, v182
	v_and_b32_e32 v248, 16, v182
	v_lshrrev_b32_e32 v248, 4, v248
	v_mul_u32_u24_e32 v248, 24, v248
	v_mov_b32_e32 v249, 0
	s_add_i32 s3, s26, s29
	v_and_b32_e32 v148, 15, v182
	v_ashrrev_i32_e32 v183, 4, v182
	v_or_b32_e32 v164, s3, v148
	s_cmp_gt_i32 s70, 1
	s_mov_b64 s[6:7], -1
	s_cbranch_scc0 .LBB0_362
	s_cmp_gt_u32 s70, 3
	s_cbranch_scc0 .LBB0_276
	s_andn2_b64 vcc, exec, s[48:49]
	s_cbranch_vccnz .LBB0_275
	v_and_or_b32 v149, v182, 7, v180
	v_and_b32_e32 v130, 0x7cf, v164
	v_cmp_gt_i32_e32 vcc, s85, v164
	v_lshlrev_b32_e32 v138, 2, v183
	v_ashrrev_i32_e32 v139, 31, v138
	v_cndmask_b32_e32 v130, v149, v130, vcc
	v_lshlrev_b32_e32 v154, 7, v130
	v_lshl_add_u64 v[130:131], s[42:43], 0, v[154:155]
	v_lshl_add_u64 v[134:135], v[138:139], 2, v[130:131]
	global_load_dwordx4 v[130:133], v[134:135], off
	s_nop 0
	global_load_dwordx4 v[134:137], v[134:135], off offset:64
	v_cmp_lt_i32_e32 vcc, s91, v164
	s_and_saveexec_b64 s[6:7], vcc
	s_xor_b64 s[6:7], exec, s[6:7]
	v_add_u32_e32 v154, 0xffff8000, v164
	v_lshlrev_b64 v[140:141], 5, v[154:155]
	v_mov_b32_e32 v165, v155
	v_lshl_add_u64 v[140:141], v[140:141], 0, s[54:55]
	v_lshlrev_b64 v[142:143], 5, v[164:165]
	s_andn2_saveexec_b64 s[6:7], s[6:7]
	v_ashrrev_i32_e32 v165, 31, v164
	v_lshlrev_b64 v[142:143], 5, v[164:165]
	v_lshl_add_u64 v[140:141], v[142:143], 0, s[56:57]
	s_or_b64 exec, exec, s[6:7]
	s_waitcnt vmcnt(0)
	v_pk_mul_f32 v[144:145], v[124:125], v[136:137]
	v_pk_mul_f32 v[166:167], v[122:123], v[134:135]
	v_pk_mul_f32 v[134:135], v[126:127], v[134:135]
	v_pk_fma_f32 v[146:147], v[128:129], v[132:133], v[144:145] neg_lo:[0,0,1] neg_hi:[0,0,1]
	v_pk_fma_f32 v[144:145], v[126:127], v[130:131], v[166:167] neg_lo:[0,0,1] neg_hi:[0,0,1]
	v_pk_mul_f32 v[136:137], v[128:129], v[136:137]
	v_pk_fma_f32 v[130:131], v[122:123], v[130:131], v[134:135]
	v_lshl_add_u64 v[134:135], v[140:141], 2, s[10:11]
	v_lshlrev_b64 v[140:141], 2, v[138:139]
	v_pk_fma_f32 v[132:133], v[124:125], v[132:133], v[136:137]
	v_lshl_add_u64 v[134:135], v[134:135], 0, v[140:141]
	global_store_dwordx4 v[134:135], v[144:147], off
	global_store_dwordx4 v[134:135], v[130:133], off offset:64
	v_cvt_pk_bf16_f32 v134, v144, v145
	v_cvt_pk_bf16_f32 v135, v146, v147
	v_cvt_pk_bf16_f32 v130, v130, v131
	v_cvt_pk_bf16_f32 v131, v132, v133
	v_lshl_add_u64 v[132:133], v[142:143], 1, s[40:41]
	v_lshl_add_u64 v[132:133], v[138:139], 1, v[132:133]
	v_or_b32_e32 v146, 16, v164
	s_movk_i32 s6, 0x7df
	v_mov_b32_e32 v240, v134
	v_mov_b32_e32 v241, v135
	v_mov_b32_e32 v242, v130
	v_mov_b32_e32 v243, v131
	s_nop 1
	v_permlane16_swap_b32_e32 v240, v242
	v_permlane16_swap_b32_e32 v241, v243
	v_lshl_add_u64 v[238:239], v[132:133], 0, v[248:249]
	global_store_dwordx4 v[238:239], v[240:243], off
	v_bitop3_b32 v130, v164, s6, 16 bitop3:0xc8
	v_cmp_gt_i32_e32 vcc, s85, v146
	s_nop 1
	v_cndmask_b32_e32 v130, v149, v130, vcc
	v_lshlrev_b32_e32 v154, 7, v130
	v_lshl_add_u64 v[130:131], s[42:43], 0, v[154:155]
	v_lshl_add_u64 v[134:135], v[130:131], 0, v[140:141]
	global_load_dwordx4 v[130:133], v[134:135], off
	s_nop 0
	global_load_dwordx4 v[134:137], v[134:135], off offset:64
	v_cmp_lt_i32_e32 vcc, s91, v146
	s_and_saveexec_b64 s[6:7], vcc
	s_xor_b64 s[6:7], exec, s[6:7]
	v_add_u32_e32 v154, 0xffff8010, v164
	v_lshlrev_b64 v[142:143], 5, v[154:155]
	v_mov_b32_e32 v147, v155
	v_lshl_add_u64 v[144:145], v[142:143], 0, s[54:55]
	v_lshlrev_b64 v[142:143], 5, v[146:147]
	s_andn2_saveexec_b64 s[6:7], s[6:7]
	v_ashrrev_i32_e32 v147, 31, v146
	v_lshlrev_b64 v[142:143], 5, v[146:147]
	v_lshl_add_u64 v[144:145], v[142:143], 0, s[56:57]
	s_or_b64 exec, exec, s[6:7]
	s_waitcnt vmcnt(0)
	v_pk_mul_f32 v[166:167], v[106:107], v[134:135]
	v_pk_mul_f32 v[134:135], v[110:111], v[134:135]
	v_pk_mul_f32 v[146:147], v[108:109], v[136:137]
	v_pk_fma_f32 v[166:167], v[110:111], v[130:131], v[166:167] neg_lo:[0,0,1] neg_hi:[0,0,1]
	v_pk_mul_f32 v[136:137], v[112:113], v[136:137]
	v_pk_fma_f32 v[130:131], v[106:107], v[130:131], v[134:135]
	v_lshl_add_u64 v[134:135], v[144:145], 2, s[10:11]
	v_pk_fma_f32 v[168:169], v[112:113], v[132:133], v[146:147] neg_lo:[0,0,1] neg_hi:[0,0,1]
	v_pk_fma_f32 v[132:133], v[108:109], v[132:133], v[136:137]
	v_lshl_add_u64 v[134:135], v[134:135], 0, v[140:141]
	global_store_dwordx4 v[134:135], v[166:169], off
	global_store_dwordx4 v[134:135], v[130:133], off offset:64
	v_cvt_pk_bf16_f32 v134, v166, v167
	v_cvt_pk_bf16_f32 v135, v168, v169
	v_cvt_pk_bf16_f32 v130, v130, v131
	v_cvt_pk_bf16_f32 v131, v132, v133
	v_lshl_add_u64 v[132:133], v[142:143], 1, s[40:41]
	v_lshl_add_u64 v[132:133], v[138:139], 1, v[132:133]
	v_or_b32_e32 v146, 32, v164
	s_movk_i32 s6, 0x7ef
	v_mov_b32_e32 v244, v134
	v_mov_b32_e32 v245, v135
	v_mov_b32_e32 v246, v130
	v_mov_b32_e32 v247, v131
	s_nop 1
	v_permlane16_swap_b32_e32 v244, v246
	v_permlane16_swap_b32_e32 v245, v247
	v_lshl_add_u64 v[234:235], v[132:133], 0, v[248:249]
	global_store_dwordx4 v[234:235], v[244:247], off
	v_bitop3_b32 v130, v164, s6, 32 bitop3:0xc8
	v_cmp_gt_i32_e32 vcc, s85, v146
	s_nop 1
	v_cndmask_b32_e32 v130, v149, v130, vcc
	v_lshlrev_b32_e32 v154, 7, v130
	v_lshl_add_u64 v[130:131], s[42:43], 0, v[154:155]
	v_lshl_add_u64 v[134:135], v[130:131], 0, v[140:141]
	global_load_dwordx4 v[130:133], v[134:135], off
	s_nop 0
	global_load_dwordx4 v[134:137], v[134:135], off offset:64
	v_cmp_lt_i32_e32 vcc, s91, v146
	s_and_saveexec_b64 s[6:7], vcc
	s_xor_b64 s[6:7], exec, s[6:7]
	v_add_u32_e32 v154, 0xffff8020, v164
	v_lshlrev_b64 v[142:143], 5, v[154:155]
	v_mov_b32_e32 v147, v155
	v_lshl_add_u64 v[144:145], v[142:143], 0, s[54:55]
	v_lshlrev_b64 v[142:143], 5, v[146:147]
	s_andn2_saveexec_b64 s[6:7], s[6:7]
	v_ashrrev_i32_e32 v147, 31, v146
	v_lshlrev_b64 v[142:143], 5, v[146:147]
	v_lshl_add_u64 v[144:145], v[142:143], 0, s[56:57]
	s_or_b64 exec, exec, s[6:7]
	s_waitcnt vmcnt(0)
; __device__ __forceinline__ unsigned pk2(float lo, float hi) { f32x2_t v = {lo, hi}; bf16x2_t b = __builtin_convertvector(v, bf16x2_t); return __builtin_bit_cast(unsigned, b); }
;     __device__ __forceinline__ void operator()(const f32x4 (&acc)[2][2][4][2], const Unit& u, int wr, int wc, int fr, int fq) const {
;     ...
;         } else if (wc == 0) {
; #pragma unroll
;             for (int ai = 0; ai < 2; ++ai)
; #pragma unroll
;                 for (int m = 0; m < 4; ++m) { const int row = row0 + ai * HALF + m * 16; const float* rp = rope + posidx(row) * 32 + 4 * fq;
;                     const f32x4 v0 = acc[ai][0][m][0], v1 = acc[ai][0][m][1], c = *(const f32x4*)rp, s = *(const f32x4*)(rp + 16); const f32x4 o0 = v0 * c - v1 * s, o1 = v1 * c + v0 * s;
;                     float* ko = out + (row < NPR ? O_KRP + (size_t)row * 32 : O_KRS + (size_t)(row - NPR) * 32) + 4 * fq; *(f32x4*)ko = o0; *(f32x4*)(ko + 16) = o1;
;                     u32x2 w0, w1; w0.x = pk2(o0[0], o0[1]); w0.y = pk2(o0[2], o0[3]); w1.x = pk2(o1[0], o1[1]); w1.y = pk2(o1[2], o1[3]);
;                     *(u32x2*)(KRB + (size_t)row * 32 + 4 * fq) = w0; *(u32x2*)(KRB + (size_t)row * 32 + 16 + 4 * fq) = w1; }
	v_pk_mul_f32 v[166:167], v[90:91], v[134:135]
	v_pk_mul_f32 v[134:135], v[94:95], v[134:135]
	v_pk_mul_f32 v[146:147], v[92:93], v[136:137]
	v_pk_fma_f32 v[166:167], v[94:95], v[130:131], v[166:167] neg_lo:[0,0,1] neg_hi:[0,0,1]
	v_pk_mul_f32 v[136:137], v[96:97], v[136:137]
	v_pk_fma_f32 v[130:131], v[90:91], v[130:131], v[134:135]
	v_lshl_add_u64 v[134:135], v[144:145], 2, s[10:11]
	v_pk_fma_f32 v[168:169], v[96:97], v[132:133], v[146:147] neg_lo:[0,0,1] neg_hi:[0,0,1]
	v_pk_fma_f32 v[132:133], v[92:93], v[132:133], v[136:137]
	v_lshl_add_u64 v[134:135], v[134:135], 0, v[140:141]
	global_store_dwordx4 v[134:135], v[166:169], off
	global_store_dwordx4 v[134:135], v[130:133], off offset:64
	v_cvt_pk_bf16_f32 v134, v166, v167
	v_cvt_pk_bf16_f32 v135, v168, v169
	v_cvt_pk_bf16_f32 v130, v130, v131
	v_cvt_pk_bf16_f32 v131, v132, v133
	v_lshl_add_u64 v[132:133], v[142:143], 1, s[40:41]
	v_lshl_add_u64 v[132:133], v[138:139], 1, v[132:133]
	v_or_b32_e32 v146, 48, v164
	s_movk_i32 s6, 0x7ff
	v_mov_b32_e32 v226, v134
	v_mov_b32_e32 v227, v135
	v_mov_b32_e32 v228, v130
	v_mov_b32_e32 v229, v131
	s_nop 1
	v_permlane16_swap_b32_e32 v226, v228
	v_permlane16_swap_b32_e32 v227, v229
	v_lshl_add_u64 v[224:225], v[132:133], 0, v[248:249]
	global_store_dwordx4 v[224:225], v[226:229], off
	v_bitop3_b32 v130, v164, s6, 48 bitop3:0xc8
	v_cmp_gt_i32_e32 vcc, s85, v146
	s_nop 1
	v_cndmask_b32_e32 v130, v149, v130, vcc
	v_lshlrev_b32_e32 v154, 7, v130
	v_lshl_add_u64 v[130:131], s[42:43], 0, v[154:155]
	v_lshl_add_u64 v[134:135], v[130:131], 0, v[140:141]
	global_load_dwordx4 v[130:133], v[134:135], off
	s_nop 0
	global_load_dwordx4 v[134:137], v[134:135], off offset:64
	v_cmp_lt_i32_e32 vcc, s91, v146
	s_and_saveexec_b64 s[6:7], vcc
	s_xor_b64 s[6:7], exec, s[6:7]
	v_add_u32_e32 v154, 0xffff8030, v164
	v_lshlrev_b64 v[142:143], 5, v[154:155]
	v_mov_b32_e32 v147, v155
	v_lshl_add_u64 v[144:145], v[142:143], 0, s[54:55]
	v_lshlrev_b64 v[142:143], 5, v[146:147]
	s_andn2_saveexec_b64 s[6:7], s[6:7]
	v_ashrrev_i32_e32 v147, 31, v146
	v_lshlrev_b64 v[142:143], 5, v[146:147]
	v_lshl_add_u64 v[144:145], v[142:143], 0, s[56:57]
	s_or_b64 exec, exec, s[6:7]
	s_waitcnt vmcnt(0)
	v_pk_mul_f32 v[166:167], v[74:75], v[134:135]
	v_pk_mul_f32 v[134:135], v[78:79], v[134:135]
	v_pk_mul_f32 v[146:147], v[76:77], v[136:137]
	v_pk_fma_f32 v[166:167], v[78:79], v[130:131], v[166:167] neg_lo:[0,0,1] neg_hi:[0,0,1]
	v_pk_mul_f32 v[136:137], v[80:81], v[136:137]
	v_pk_fma_f32 v[130:131], v[74:75], v[130:131], v[134:135]
	v_lshl_add_u64 v[134:135], v[144:145], 2, s[10:11]
	v_pk_fma_f32 v[168:169], v[80:81], v[132:133], v[146:147] neg_lo:[0,0,1] neg_hi:[0,0,1]
	v_pk_fma_f32 v[132:133], v[76:77], v[132:133], v[136:137]
	v_lshl_add_u64 v[134:135], v[134:135], 0, v[140:141]
	global_store_dwordx4 v[134:135], v[166:169], off
	global_store_dwordx4 v[134:135], v[130:133], off offset:64
	v_cvt_pk_bf16_f32 v134, v166, v167
	v_cvt_pk_bf16_f32 v135, v168, v169
	v_cvt_pk_bf16_f32 v130, v130, v131
	v_cvt_pk_bf16_f32 v131, v132, v133
	v_lshl_add_u64 v[132:133], v[142:143], 1, s[40:41]
	v_lshl_add_u64 v[132:133], v[138:139], 1, v[132:133]
	v_add_u32_e32 v146, 0x80, v164
	s_movk_i32 s6, 0x7f80
	v_mov_b32_e32 v230, v134
	v_mov_b32_e32 v231, v135
	v_mov_b32_e32 v232, v130
	v_mov_b32_e32 v233, v131
	s_nop 1
	v_permlane16_swap_b32_e32 v230, v232
	v_permlane16_swap_b32_e32 v231, v233
	v_lshl_add_u64 v[222:223], v[132:133], 0, v[248:249]
	global_store_dwordx4 v[222:223], v[230:233], off
	v_and_b32_e32 v130, 0x7cf, v146
	v_cmp_gt_i32_e32 vcc, s6, v164
	s_nop 1
	v_cndmask_b32_e32 v130, v149, v130, vcc
	v_lshlrev_b32_e32 v154, 7, v130
	v_lshl_add_u64 v[130:131], s[42:43], 0, v[154:155]
	v_lshl_add_u64 v[134:135], v[130:131], 0, v[140:141]
	global_load_dwordx4 v[130:133], v[134:135], off
	s_nop 0
	global_load_dwordx4 v[134:137], v[134:135], off offset:64
	v_cmp_lt_i32_e32 vcc, s92, v164
	s_and_saveexec_b64 s[6:7], vcc
	s_xor_b64 s[6:7], exec, s[6:7]
	v_add_u32_e32 v154, 0xffff8080, v164
	v_lshlrev_b64 v[142:143], 5, v[154:155]
	v_mov_b32_e32 v147, v155
	v_lshl_add_u64 v[144:145], v[142:143], 0, s[54:55]
	v_lshlrev_b64 v[142:143], 5, v[146:147]
	s_andn2_saveexec_b64 s[6:7], s[6:7]
	v_ashrrev_i32_e32 v147, 31, v146
	v_lshlrev_b64 v[142:143], 5, v[146:147]
	v_lshl_add_u64 v[144:145], v[142:143], 0, s[56:57]
	s_or_b64 exec, exec, s[6:7]
	s_waitcnt vmcnt(0)
	v_pk_mul_f32 v[166:167], v[58:59], v[134:135]
	v_pk_mul_f32 v[134:135], v[62:63], v[134:135]
	v_pk_mul_f32 v[146:147], v[60:61], v[136:137]
	v_pk_fma_f32 v[166:167], v[62:63], v[130:131], v[166:167] neg_lo:[0,0,1] neg_hi:[0,0,1]
	v_pk_mul_f32 v[136:137], v[64:65], v[136:137]
	v_pk_fma_f32 v[130:131], v[58:59], v[130:131], v[134:135]
	v_lshl_add_u64 v[134:135], v[144:145], 2, s[10:11]
	v_pk_fma_f32 v[168:169], v[64:65], v[132:133], v[146:147] neg_lo:[0,0,1] neg_hi:[0,0,1]
	v_pk_fma_f32 v[132:133], v[60:61], v[132:133], v[136:137]
	v_lshl_add_u64 v[134:135], v[134:135], 0, v[140:141]
	global_store_dwordx4 v[134:135], v[166:169], off
	global_store_dwordx4 v[134:135], v[130:133], off offset:64
	v_cvt_pk_bf16_f32 v134, v166, v167
	v_cvt_pk_bf16_f32 v135, v168, v169
	v_cvt_pk_bf16_f32 v130, v130, v131
	v_cvt_pk_bf16_f32 v131, v132, v133
	v_lshl_add_u64 v[132:133], v[142:143], 1, s[40:41]
	v_lshl_add_u64 v[132:133], v[138:139], 1, v[132:133]
	v_add_u32_e32 v146, 0x90, v164
	s_movk_i32 s6, 0x7f70
	v_mov_b32_e32 v240, v134
	v_mov_b32_e32 v241, v135
	v_mov_b32_e32 v242, v130
	v_mov_b32_e32 v243, v131
	s_nop 1
	v_permlane16_swap_b32_e32 v240, v242
	v_permlane16_swap_b32_e32 v241, v243
	v_lshl_add_u64 v[238:239], v[132:133], 0, v[248:249]
	global_store_dwordx4 v[238:239], v[240:243], off
	v_and_b32_e32 v130, 0x7df, v146
	v_cmp_gt_i32_e32 vcc, s6, v164
	s_nop 1
	v_cndmask_b32_e32 v130, v149, v130, vcc
	v_lshlrev_b32_e32 v154, 7, v130
	v_lshl_add_u64 v[130:131], s[42:43], 0, v[154:155]
	v_lshl_add_u64 v[134:135], v[130:131], 0, v[140:141]
	global_load_dwordx4 v[130:133], v[134:135], off
	s_nop 0
	global_load_dwordx4 v[134:137], v[134:135], off offset:64
	v_cmp_lt_i32_e32 vcc, s93, v164
	s_and_saveexec_b64 s[6:7], vcc
	s_xor_b64 s[6:7], exec, s[6:7]
	v_add_u32_e32 v154, 0xffff8090, v164
	v_lshlrev_b64 v[142:143], 5, v[154:155]
	v_mov_b32_e32 v147, v155
	v_lshl_add_u64 v[144:145], v[142:143], 0, s[54:55]
	v_lshlrev_b64 v[142:143], 5, v[146:147]
	s_andn2_saveexec_b64 s[6:7], s[6:7]
	v_ashrrev_i32_e32 v147, 31, v146
	v_lshlrev_b64 v[142:143], 5, v[146:147]
	v_lshl_add_u64 v[144:145], v[142:143], 0, s[56:57]
	s_or_b64 exec, exec, s[6:7]
	s_waitcnt vmcnt(0)
; __device__ __forceinline__ unsigned pk2(float lo, float hi) { f32x2_t v = {lo, hi}; bf16x2_t b = __builtin_convertvector(v, bf16x2_t); return __builtin_bit_cast(unsigned, b); }
;     __device__ __forceinline__ void operator()(const f32x4 (&acc)[2][2][4][2], const Unit& u, int wr, int wc, int fr, int fq) const {
;     ...
;         } else if (wc == 0) {
; #pragma unroll
;             for (int ai = 0; ai < 2; ++ai)
; #pragma unroll
;                 for (int m = 0; m < 4; ++m) { const int row = row0 + ai * HALF + m * 16; const float* rp = rope + posidx(row) * 32 + 4 * fq;
;                     const f32x4 v0 = acc[ai][0][m][0], v1 = acc[ai][0][m][1], c = *(const f32x4*)rp, s = *(const f32x4*)(rp + 16); const f32x4 o0 = v0 * c - v1 * s, o1 = v1 * c + v0 * s;
;                     float* ko = out + (row < NPR ? O_KRP + (size_t)row * 32 : O_KRS + (size_t)(row - NPR) * 32) + 4 * fq; *(f32x4*)ko = o0; *(f32x4*)(ko + 16) = o1;
;                     u32x2 w0, w1; w0.x = pk2(o0[0], o0[1]); w0.y = pk2(o0[2], o0[3]); w1.x = pk2(o1[0], o1[1]); w1.y = pk2(o1[2], o1[3]);
;                     *(u32x2*)(KRB + (size_t)row * 32 + 4 * fq) = w0; *(u32x2*)(KRB + (size_t)row * 32 + 16 + 4 * fq) = w1; }
	v_pk_mul_f32 v[166:167], v[42:43], v[134:135]
	v_pk_mul_f32 v[134:135], v[46:47], v[134:135]
	v_pk_mul_f32 v[146:147], v[44:45], v[136:137]
	v_pk_fma_f32 v[166:167], v[46:47], v[130:131], v[166:167] neg_lo:[0,0,1] neg_hi:[0,0,1]
	v_pk_mul_f32 v[136:137], v[48:49], v[136:137]
	v_pk_fma_f32 v[130:131], v[42:43], v[130:131], v[134:135]
	v_lshl_add_u64 v[134:135], v[144:145], 2, s[10:11]
	v_pk_fma_f32 v[168:169], v[48:49], v[132:133], v[146:147] neg_lo:[0,0,1] neg_hi:[0,0,1]
	v_pk_fma_f32 v[132:133], v[44:45], v[132:133], v[136:137]
	v_lshl_add_u64 v[134:135], v[134:135], 0, v[140:141]
	global_store_dwordx4 v[134:135], v[166:169], off
	global_store_dwordx4 v[134:135], v[130:133], off offset:64
	v_cvt_pk_bf16_f32 v134, v166, v167
	v_cvt_pk_bf16_f32 v135, v168, v169
	v_cvt_pk_bf16_f32 v130, v130, v131
	v_cvt_pk_bf16_f32 v131, v132, v133
	v_lshl_add_u64 v[132:133], v[142:143], 1, s[40:41]
	v_lshl_add_u64 v[132:133], v[138:139], 1, v[132:133]
	v_add_u32_e32 v146, 0xa0, v164
	s_movk_i32 s6, 0x7f60
	v_mov_b32_e32 v244, v134
	v_mov_b32_e32 v245, v135
	v_mov_b32_e32 v246, v130
	v_mov_b32_e32 v247, v131
	s_nop 1
	v_permlane16_swap_b32_e32 v244, v246
	v_permlane16_swap_b32_e32 v245, v247
	v_lshl_add_u64 v[234:235], v[132:133], 0, v[248:249]
	global_store_dwordx4 v[234:235], v[244:247], off
	v_and_b32_e32 v130, 0x7ef, v146
	v_cmp_gt_i32_e32 vcc, s6, v164
	s_nop 1
	v_cndmask_b32_e32 v130, v149, v130, vcc
	v_lshlrev_b32_e32 v154, 7, v130
	v_lshl_add_u64 v[130:131], s[42:43], 0, v[154:155]
	v_lshl_add_u64 v[134:135], v[130:131], 0, v[140:141]
	global_load_dwordx4 v[130:133], v[134:135], off
	s_nop 0
	global_load_dwordx4 v[134:137], v[134:135], off offset:64
	v_cmp_lt_i32_e32 vcc, s94, v164
	s_and_saveexec_b64 s[6:7], vcc
	s_xor_b64 s[6:7], exec, s[6:7]
	v_add_u32_e32 v154, 0xffff80a0, v164
	v_lshlrev_b64 v[142:143], 5, v[154:155]
	v_mov_b32_e32 v147, v155
	v_lshl_add_u64 v[144:145], v[142:143], 0, s[54:55]
	v_lshlrev_b64 v[142:143], 5, v[146:147]
	s_andn2_saveexec_b64 s[6:7], s[6:7]
	v_ashrrev_i32_e32 v147, 31, v146
	v_lshlrev_b64 v[142:143], 5, v[146:147]
	v_lshl_add_u64 v[144:145], v[142:143], 0, s[56:57]
	s_or_b64 exec, exec, s[6:7]
	s_waitcnt vmcnt(0)
	v_pk_mul_f32 v[166:167], v[26:27], v[134:135]
	v_pk_mul_f32 v[134:135], v[30:31], v[134:135]
	v_pk_mul_f32 v[146:147], v[28:29], v[136:137]
	v_pk_fma_f32 v[166:167], v[30:31], v[130:131], v[166:167] neg_lo:[0,0,1] neg_hi:[0,0,1]
	v_pk_mul_f32 v[136:137], v[32:33], v[136:137]
	v_pk_fma_f32 v[130:131], v[26:27], v[130:131], v[134:135]
	v_lshl_add_u64 v[134:135], v[144:145], 2, s[10:11]
	v_pk_fma_f32 v[168:169], v[32:33], v[132:133], v[146:147] neg_lo:[0,0,1] neg_hi:[0,0,1]
	v_pk_fma_f32 v[132:133], v[28:29], v[132:133], v[136:137]
	v_lshl_add_u64 v[134:135], v[134:135], 0, v[140:141]
	global_store_dwordx4 v[134:135], v[166:169], off
	global_store_dwordx4 v[134:135], v[130:133], off offset:64
	v_cvt_pk_bf16_f32 v134, v166, v167
	v_cvt_pk_bf16_f32 v135, v168, v169
	v_cvt_pk_bf16_f32 v130, v130, v131
	v_cvt_pk_bf16_f32 v131, v132, v133
	v_lshl_add_u64 v[132:133], v[142:143], 1, s[40:41]
	v_lshl_add_u64 v[132:133], v[138:139], 1, v[132:133]
	v_add_u32_e32 v144, 0xb0, v164
	v_mov_b32_e32 v226, v134
	v_mov_b32_e32 v227, v135
	v_mov_b32_e32 v228, v130
	v_mov_b32_e32 v229, v131
	s_nop 1
	v_permlane16_swap_b32_e32 v226, v228
	v_permlane16_swap_b32_e32 v227, v229
	v_lshl_add_u64 v[224:225], v[132:133], 0, v[248:249]
	global_store_dwordx4 v[224:225], v[226:229], off
	v_and_b32_e32 v130, 0x7ff, v144
	v_cmp_gt_i32_e32 vcc, s95, v164
	s_movk_i32 s6, 0x7f4f
	s_nop 0
	v_cndmask_b32_e32 v130, v149, v130, vcc
	v_lshlrev_b32_e32 v154, 7, v130
	v_lshl_add_u64 v[130:131], s[42:43], 0, v[154:155]
	v_lshl_add_u64 v[134:135], v[130:131], 0, v[140:141]
	global_load_dwordx4 v[130:133], v[134:135], off
	s_nop 0
	global_load_dwordx4 v[134:137], v[134:135], off offset:64
	v_cmp_lt_i32_e32 vcc, s6, v164
	s_and_saveexec_b64 s[6:7], vcc
	s_xor_b64 s[6:7], exec, s[6:7]
	v_add_u32_e32 v154, 0xffff80b0, v164
	v_lshlrev_b64 v[140:141], 5, v[154:155]
	v_mov_b32_e32 v145, v155
	v_lshl_add_u64 v[142:143], v[140:141], 0, s[54:55]
	v_lshlrev_b64 v[140:141], 5, v[144:145]
	s_andn2_saveexec_b64 s[6:7], s[6:7]
	v_ashrrev_i32_e32 v145, 31, v144
	v_lshlrev_b64 v[140:141], 5, v[144:145]
	v_lshl_add_u64 v[142:143], v[140:141], 0, s[56:57]
	s_or_b64 exec, exec, s[6:7]
	s_waitcnt vmcnt(0)
	v_pk_mul_f32 v[144:145], v[12:13], v[136:137]
	v_pk_mul_f32 v[166:167], v[10:11], v[134:135]
	v_pk_mul_f32 v[134:135], v[14:15], v[134:135]
	v_pk_fma_f32 v[146:147], v[16:17], v[132:133], v[144:145] neg_lo:[0,0,1] neg_hi:[0,0,1]
	v_pk_fma_f32 v[144:145], v[14:15], v[130:131], v[166:167] neg_lo:[0,0,1] neg_hi:[0,0,1]
	v_pk_mul_f32 v[136:137], v[16:17], v[136:137]
	v_pk_fma_f32 v[130:131], v[10:11], v[130:131], v[134:135]
	v_lshl_add_u64 v[134:135], v[142:143], 2, s[10:11]
	v_pk_fma_f32 v[132:133], v[12:13], v[132:133], v[136:137]
	v_lshl_add_u64 v[134:135], v[138:139], 2, v[134:135]
	global_store_dwordx4 v[134:135], v[144:147], off
	global_store_dwordx4 v[134:135], v[130:133], off offset:64
	v_cvt_pk_bf16_f32 v134, v144, v145
	v_cvt_pk_bf16_f32 v135, v146, v147
	v_cvt_pk_bf16_f32 v130, v130, v131
	v_cvt_pk_bf16_f32 v131, v132, v133
	v_lshl_add_u64 v[132:133], v[140:141], 1, s[40:41]
	v_lshl_add_u64 v[132:133], v[138:139], 1, v[132:133]
	v_mov_b32_e32 v230, v134
	v_mov_b32_e32 v231, v135
	v_mov_b32_e32 v232, v130
	v_mov_b32_e32 v233, v131
	s_nop 1
	v_permlane16_swap_b32_e32 v230, v232
	v_permlane16_swap_b32_e32 v231, v233
	v_lshl_add_u64 v[222:223], v[132:133], 0, v[248:249]
	global_store_dwordx4 v[222:223], v[230:233], off

; #define PG8_LAS __attribute__((address_space(3)))
; __device__ __forceinline__ unsigned pk2(float lo, float hi) { f32x2_t v = {lo, hi}; bf16x2_t b = __builtin_convertvector(v, bf16x2_t); return __builtin_bit_cast(unsigned, b); }
;     __device__ __forceinline__ void operator()(const f32x4 (&acc)[2][2][4][2], const Unit& u, int wr, int wc, int fr, int fq) const {
;     ...
;             asm volatile("s_waitcnt lgkmcnt(0)" ::: "memory"); __builtin_amdgcn_s_barrier(); asm volatile("" ::: "memory");
;             const float* gv = (u.pn == 2 ? g_q : g_kv) + wc * 32 + 4 * fq;
;             f32x4 gg[2][2];
; #pragma unroll
;             for (int bj = 0; bj < 2; ++bj)
; #pragma unroll
;                 for (int n = 0; n < 2; ++n) gg[bj][n] = *(const f32x4*)(gv + bj * HALF + n * 16);
; #pragma unroll
;             for (int ai = 0; ai < 2; ++ai)
; #pragma unroll
;                 for (int m = 0; m < 4; ++m) { const int rl = ai * HALF + wr * 64 + m * 16 + fr, row = u.pm * BM + rl; const f32x4 p = *(const PG8_LAS f32x4*)(P + rl * 4);
;                     const float rstd = 1.f / sqrtf(((p[0] + p[1]) + (p[2] + p[3])) * (1.f / 256.f) + EPS); const int colb = wc * 32 + 4 * fq;
;                     if (u.pn == 2) { bf16_t* op = CQN + (size_t)row * 256 + colb;
; #pragma unroll
;                         for (int bj = 0; bj < 2; ++bj)
; #pragma unroll
;                             for (int n = 0; n < 2; ++n) { const f32x4 o = (acc[ai][bj][m][n] * rstd) * gg[bj][n]; u32x2 w; w.x = pk2(o[0], o[1]); w.y = pk2(o[2], o[3]); *(u32x2*)(op + bj * HALF + n * 16) = w; }
;                     } else { bf16_t* op = LAT + (size_t)row * 256 + colb; float* fo = out + (row < NPR ? O_LATP + (size_t)row * 256 : O_LATS + (size_t)(row - NPR) * 256) + colb;
; #pragma unroll
;                         for (int bj = 0; bj < 2; ++bj)
; #pragma unroll
;                             for (int n = 0; n < 2; ++n) { const f32x4 o = (acc[ai][bj][m][n] * rstd) * gg[bj][n]; *(f32x4*)(fo + bj * HALF + n * 16) = o; u32x2 w; w.x = pk2(o[0], o[1]); w.y = pk2(o[2], o[3]); *(u32x2*)(op + bj * HALF + n * 16) = w; } } }
.LBB0_295:
	s_or_b64 exec, exec, s[6:7]
	s_cmp_lg_u32 s70, 2
	s_cselect_b64 s[8:9], -1, 0
	s_cmp_eq_u32 s70, 2
	s_cselect_b32 s6, s14, s16
	s_cselect_b32 s7, s15, s17
	s_add_u32 s6, s6, s96
	v_lshlrev_b32_e32 v166, 2, v183
	s_addc_u32 s7, s7, 0
	v_ashrrev_i32_e32 v167, 31, v166
	s_waitcnt lgkmcnt(0)
	s_barrier
	s_waitcnt lgkmcnt(0)
	v_lshl_add_u64 v[130:131], v[166:167], 2, s[6:7]
	global_load_dwordx4 v[142:145], v[130:131], off
	global_load_dwordx4 v[138:141], v[130:131], off offset:64
	global_load_dwordx4 v[134:137], v[130:131], off offset:512
	s_nop 0
	global_load_dwordx4 v[130:133], v[130:131], off offset:576
	v_add_u32_e32 v146, 0, v146
	v_add_u32_e32 v146, 0x20400, v146
	ds_read_b128 v[146:149], v146
	v_add_u32_e32 v172, s26, v165
	v_ashrrev_i32_e32 v173, 31, v172
	s_waitcnt lgkmcnt(0)
	v_add_f32_e32 v146, v146, v147
	v_add_f32_e32 v147, v148, v149
	v_add_f32_e32 v146, v146, v147
	v_fmamk_f32 v146, v146, 0x3b800000, v178
	v_mul_f32_e32 v147, 0x4f800000, v146
	v_cmp_gt_f32_e32 vcc, s97, v146
	s_nop 1
	v_cndmask_b32_e32 v146, v146, v147, vcc
	v_sqrt_f32_e32 v147, v146
	s_nop 0
	v_add_u32_e32 v148, -1, v147
	v_fma_f32 v149, -v148, v147, v146
	v_cmp_ge_f32_e64 s[6:7], 0, v149
	v_add_u32_e32 v149, 1, v147
	s_nop 0
	v_cndmask_b32_e64 v148, v147, v148, s[6:7]
	v_fma_f32 v147, -v149, v147, v146
	v_cmp_lt_f32_e64 s[6:7], 0, v147
	s_nop 1
	v_cndmask_b32_e64 v147, v148, v149, s[6:7]
	v_mul_f32_e32 v148, 0x37800000, v147
	v_cndmask_b32_e32 v147, v147, v148, vcc
	v_cmp_class_f32_e32 vcc, v146, v179
	s_nop 1
	v_cndmask_b32_e32 v146, v147, v146, vcc
	v_div_scale_f32 v147, s[6:7], v146, v146, 1.0
	v_rcp_f32_e32 v148, v147
	v_readlane_b32 s6, v237, 10
	v_fma_f32 v149, -v147, v148, 1.0
	v_fmac_f32_e32 v148, v149, v148
	v_div_scale_f32 v149, vcc, 1.0, v146, 1.0
	v_mul_f32_e32 v154, v149, v148
	v_fma_f32 v168, -v147, v154, v149
	v_fmac_f32_e32 v154, v168, v148
	v_fma_f32 v147, -v147, v154, v149
	v_add_u32_e32 v166, s6, v166
	v_div_fmas_f32 v147, v147, v148, v154
	v_ashrrev_i32_e32 v167, 31, v166
	v_div_fixup_f32 v168, v147, v146, 1.0
	s_mov_b64 s[6:7], -1
	s_and_b64 vcc, exec, s[8:9]
	s_cbranch_vccz .LBB0_301
	v_cmp_lt_i32_e32 vcc, s91, v172
	s_and_saveexec_b64 s[6:7], vcc
	s_xor_b64 s[6:7], exec, s[6:7]
	v_add_u32_e32 v154, 0xffff8000, v172
	v_lshlrev_b64 v[146:147], 8, v[154:155]
	v_lshl_add_u64 v[146:147], v[146:147], 0, s[58:59]
	s_or_saveexec_b64 s[6:7], s[6:7]
	v_lshlrev_b64 v[148:149], 8, v[172:173]
	s_xor_b64 exec, exec, s[6:7]
	v_lshl_add_u64 v[146:147], v[148:149], 0, s[60:61]
	s_or_b64 exec, exec, s[6:7]
	v_lshl_add_u64 v[146:147], v[146:147], 2, s[10:11]
	v_lshl_add_u64 v[186:187], v[166:167], 2, v[146:147]
	v_pk_mul_f32 v[146:147], v[128:129], v[168:169] op_sel_hi:[1,0]
	v_pk_mul_f32 v[188:189], v[126:127], v[168:169] op_sel_hi:[1,0]
	v_lshl_add_u64 v[170:171], v[148:149], 1, s[38:39]
	s_waitcnt vmcnt(0)
	v_pk_mul_f32 v[148:149], v[144:145], v[146:147]
	v_pk_mul_f32 v[146:147], v[142:143], v[188:189]
	v_lshl_add_u64 v[184:185], v[166:167], 1, v[170:171]
	global_store_dwordx4 v[186:187], v[146:149], off
	v_pk_mul_f32 v[188:189], v[122:123], v[168:169] op_sel_hi:[1,0]
	s_mov_b64 s[6:7], 0
	v_cvt_pk_bf16_f32 v146, v146, v147
	v_cvt_pk_bf16_f32 v147, v148, v149
	v_mov_b32_e32 v240, v146
	v_mov_b32_e32 v241, v147
	v_pk_mul_f32 v[146:147], v[124:125], v[168:169] op_sel_hi:[1,0]
	s_nop 0
	v_pk_mul_f32 v[148:149], v[140:141], v[146:147]
	v_pk_mul_f32 v[146:147], v[138:139], v[188:189]
	global_store_dwordx4 v[186:187], v[146:149], off offset:64
	v_pk_mul_f32 v[188:189], v[118:119], v[168:169] op_sel_hi:[1,0]
	s_nop 0
	v_cvt_pk_bf16_f32 v146, v146, v147
	v_cvt_pk_bf16_f32 v147, v148, v149
	v_mov_b32_e32 v242, v146
	v_mov_b32_e32 v243, v147
	s_nop 1
	v_permlane16_swap_b32_e32 v240, v242
	v_permlane16_swap_b32_e32 v241, v243
	v_lshl_add_u64 v[238:239], v[184:185], 0, v[248:249]
	global_store_dwordx4 v[238:239], v[240:243], off
	v_pk_mul_f32 v[146:147], v[120:121], v[168:169] op_sel_hi:[1,0]
	s_nop 0
	v_pk_mul_f32 v[148:149], v[136:137], v[146:147]
	v_pk_mul_f32 v[146:147], v[134:135], v[188:189]
	global_store_dwordx4 v[186:187], v[146:149], off offset:512
	s_nop 1
	v_cvt_pk_bf16_f32 v146, v146, v147
	v_cvt_pk_bf16_f32 v147, v148, v149
	global_store_dwordx2 v[184:185], v[146:147], off offset:256
	v_pk_mul_f32 v[146:147], v[116:117], v[168:169] op_sel_hi:[1,0]
	v_pk_mul_f32 v[184:185], v[114:115], v[168:169] op_sel_hi:[1,0]
	v_pk_mul_f32 v[148:149], v[132:133], v[146:147]
	v_pk_mul_f32 v[146:147], v[130:131], v[184:185]
	global_store_dwordx4 v[186:187], v[146:149], off offset:576
.LBB0_301:
	s_and_b64 vcc, exec, s[6:7]
	s_cbranch_vccz .LBB0_303
	v_lshlrev_b64 v[146:147], 9, v[172:173]
	v_pk_mul_f32 v[148:149], v[128:129], v[168:169] op_sel_hi:[1,0]
	v_pk_mul_f32 v[172:173], v[126:127], v[168:169] op_sel_hi:[1,0]
	v_lshl_add_u64 v[170:171], s[36:37], 0, v[146:147]
	s_waitcnt vmcnt(0)
	v_pk_mul_f32 v[148:149], v[144:145], v[148:149]
	v_pk_mul_f32 v[172:173], v[142:143], v[172:173]
	v_lshl_add_u64 v[146:147], v[166:167], 1, v[170:171]
	v_cvt_pk_bf16_f32 v172, v172, v173
	v_cvt_pk_bf16_f32 v173, v148, v149
	v_mov_b32_e32 v244, v172
	v_mov_b32_e32 v245, v173
	v_pk_mul_f32 v[148:149], v[124:125], v[168:169] op_sel_hi:[1,0]
	v_pk_mul_f32 v[172:173], v[122:123], v[168:169] op_sel_hi:[1,0]
	v_pk_mul_f32 v[148:149], v[140:141], v[148:149]
	v_pk_mul_f32 v[172:173], v[138:139], v[172:173]
	s_nop 0
	v_cvt_pk_bf16_f32 v172, v172, v173
	v_cvt_pk_bf16_f32 v173, v148, v149
	v_mov_b32_e32 v246, v172
	v_mov_b32_e32 v247, v173
	s_nop 1
	v_permlane16_swap_b32_e32 v244, v246
	v_permlane16_swap_b32_e32 v245, v247
	v_lshl_add_u64 v[234:235], v[146:147], 0, v[248:249]
	global_store_dwordx4 v[234:235], v[244:247], off
	v_pk_mul_f32 v[148:149], v[120:121], v[168:169] op_sel_hi:[1,0]
	v_pk_mul_f32 v[172:173], v[118:119], v[168:169] op_sel_hi:[1,0]
	v_pk_mul_f32 v[148:149], v[136:137], v[148:149]
	v_pk_mul_f32 v[172:173], v[134:135], v[172:173]
	s_nop 0
	v_cvt_pk_bf16_f32 v172, v172, v173
	v_cvt_pk_bf16_f32 v173, v148, v149
	global_store_dwordx2 v[146:147], v[172:173], off offset:256
	v_pk_mul_f32 v[146:147], v[116:117], v[168:169] op_sel_hi:[1,0]
	v_pk_mul_f32 v[168:169], v[114:115], v[168:169] op_sel_hi:[1,0]
	v_pk_mul_f32 v[148:149], v[132:133], v[146:147]
	v_pk_mul_f32 v[146:147], v[130:131], v[168:169]
; #define PG8_LAS __attribute__((address_space(3)))
; __device__ __forceinline__ unsigned pk2(float lo, float hi) { f32x2_t v = {lo, hi}; bf16x2_t b = __builtin_convertvector(v, bf16x2_t); return __builtin_bit_cast(unsigned, b); }
;     __device__ __forceinline__ void operator()(const f32x4 (&acc)[2][2][4][2], const Unit& u, int wr, int wc, int fr, int fq) const {
;     ...
;             for (int ai = 0; ai < 2; ++ai)
; #pragma unroll
;                 for (int m = 0; m < 4; ++m) { const int rl = ai * HALF + wr * 64 + m * 16 + fr, row = u.pm * BM + rl; const f32x4 p = *(const PG8_LAS f32x4*)(P + rl * 4);
;                     const float rstd = 1.f / sqrtf(((p[0] + p[1]) + (p[2] + p[3])) * (1.f / 256.f) + EPS); const int colb = wc * 32 + 4 * fq;
;                     if (u.pn == 2) { bf16_t* op = CQN + (size_t)row * 256 + colb;
; #pragma unroll
;                         for (int bj = 0; bj < 2; ++bj)
; #pragma unroll
;                             for (int n = 0; n < 2; ++n) { const f32x4 o = (acc[ai][bj][m][n] * rstd) * gg[bj][n]; u32x2 w; w.x = pk2(o[0], o[1]); w.y = pk2(o[2], o[3]); *(u32x2*)(op + bj * HALF + n * 16) = w; }
;                     } else { bf16_t* op = LAT + (size_t)row * 256 + colb; float* fo = out + (row < NPR ? O_LATP + (size_t)row * 256 : O_LATS + (size_t)(row - NPR) * 256) + colb;
; #pragma unroll
;                         for (int bj = 0; bj < 2; ++bj)
; #pragma unroll
;                             for (int n = 0; n < 2; ++n) { const f32x4 o = (acc[ai][bj][m][n] * rstd) * gg[bj][n]; *(f32x4*)(fo + bj * HALF + n * 16) = o; u32x2 w; w.x = pk2(o[0], o[1]); w.y = pk2(o[2], o[3]); *(u32x2*)(op + bj * HALF + n * 16) = w; } } }
.LBB0_303:
	v_lshl_add_u64 v[168:169], v[166:167], 1, v[170:171]
	v_cvt_pk_bf16_f32 v146, v146, v147
	v_cvt_pk_bf16_f32 v147, v148, v149
	global_store_dwordx2 v[168:169], v[146:147], off offset:288
	v_or_b32_e32 v146, 16, v165
	v_add_u32_e32 v168, s26, v146
	v_lshl_add_u32 v146, v146, 4, 0
	v_add_u32_e32 v146, 0x20400, v146
	ds_read_b128 v[146:149], v146
	s_mov_b64 s[72:73], -1
	s_waitcnt lgkmcnt(0)
	v_add_f32_e32 v146, v146, v147
	v_add_f32_e32 v147, v148, v149
	v_add_f32_e32 v146, v146, v147
	v_fmamk_f32 v146, v146, 0x3b800000, v178
	v_cmp_gt_f32_e32 vcc, s97, v146
	v_mul_f32_e32 v147, 0x4f800000, v146
	s_nop 0
	v_cndmask_b32_e32 v146, v146, v147, vcc
	v_sqrt_f32_e32 v147, v146
	s_nop 0
	v_add_u32_e32 v148, -1, v147
	v_fma_f32 v149, -v148, v147, v146
	v_cmp_ge_f32_e64 s[6:7], 0, v149
	v_add_u32_e32 v149, 1, v147
	s_nop 0
	v_cndmask_b32_e64 v148, v147, v148, s[6:7]
	v_fma_f32 v147, -v149, v147, v146
	v_cmp_lt_f32_e64 s[6:7], 0, v147
	s_nop 1
	v_cndmask_b32_e64 v147, v148, v149, s[6:7]
	v_mul_f32_e32 v148, 0x37800000, v147
	v_cndmask_b32_e32 v147, v147, v148, vcc
	v_cmp_class_f32_e32 vcc, v146, v179
	s_nop 1
	v_cndmask_b32_e32 v146, v147, v146, vcc
	v_div_scale_f32 v147, s[6:7], v146, v146, 1.0
	v_rcp_f32_e32 v148, v147
	s_nop 0
	v_fma_f32 v149, -v147, v148, 1.0
	v_fmac_f32_e32 v148, v149, v148
	v_div_scale_f32 v149, vcc, 1.0, v146, 1.0
	v_mul_f32_e32 v154, v149, v148
	v_fma_f32 v169, -v147, v154, v149
	v_fmac_f32_e32 v154, v169, v148
	v_fma_f32 v147, -v147, v154, v149
	v_div_fmas_f32 v147, v147, v148, v154
	v_div_fixup_f32 v170, v147, v146, 1.0
	v_cndmask_b32_e64 v146, 0, 1, s[8:9]
	v_ashrrev_i32_e32 v169, 31, v168
	v_cmp_ne_u32_e64 s[6:7], 1, v146
	s_andn2_b64 vcc, exec, s[8:9]
	s_cbranch_vccnz .LBB0_309
	v_cmp_lt_i32_e32 vcc, s91, v168
	s_and_saveexec_b64 s[8:9], vcc
	s_xor_b64 s[8:9], exec, s[8:9]
	v_add_u32_e32 v154, 0xffff8000, v168
	v_lshlrev_b64 v[146:147], 8, v[154:155]
	v_lshl_add_u64 v[146:147], v[146:147], 0, s[58:59]
	s_or_saveexec_b64 s[8:9], s[8:9]
	v_lshlrev_b64 v[148:149], 8, v[168:169]
	s_xor_b64 exec, exec, s[8:9]
	v_lshl_add_u64 v[146:147], v[148:149], 0, s[60:61]
	s_or_b64 exec, exec, s[8:9]
	v_lshl_add_u64 v[146:147], v[146:147], 2, s[10:11]
	v_lshl_add_u64 v[186:187], v[166:167], 2, v[146:147]
	v_pk_mul_f32 v[146:147], v[112:113], v[170:171] op_sel_hi:[1,0]
	v_pk_mul_f32 v[188:189], v[110:111], v[170:171] op_sel_hi:[1,0]
	v_lshl_add_u64 v[172:173], v[148:149], 1, s[38:39]
	s_waitcnt vmcnt(0)
	v_pk_mul_f32 v[148:149], v[144:145], v[146:147]
	v_pk_mul_f32 v[146:147], v[142:143], v[188:189]
	v_lshl_add_u64 v[184:185], v[166:167], 1, v[172:173]
	global_store_dwordx4 v[186:187], v[146:149], off
	v_pk_mul_f32 v[188:189], v[106:107], v[170:171] op_sel_hi:[1,0]
	s_mov_b64 s[72:73], 0
	v_cvt_pk_bf16_f32 v146, v146, v147
	v_cvt_pk_bf16_f32 v147, v148, v149
	v_mov_b32_e32 v226, v146
	v_mov_b32_e32 v227, v147
	v_pk_mul_f32 v[146:147], v[108:109], v[170:171] op_sel_hi:[1,0]
	s_nop 0
	v_pk_mul_f32 v[148:149], v[140:141], v[146:147]
	v_pk_mul_f32 v[146:147], v[138:139], v[188:189]
	global_store_dwordx4 v[186:187], v[146:149], off offset:64
	v_pk_mul_f32 v[188:189], v[102:103], v[170:171] op_sel_hi:[1,0]
	s_nop 0
	v_cvt_pk_bf16_f32 v146, v146, v147
	v_cvt_pk_bf16_f32 v147, v148, v149
	v_mov_b32_e32 v228, v146
	v_mov_b32_e32 v229, v147
	s_nop 1
	v_permlane16_swap_b32_e32 v226, v228
	v_permlane16_swap_b32_e32 v227, v229
	v_lshl_add_u64 v[224:225], v[184:185], 0, v[248:249]
	global_store_dwordx4 v[224:225], v[226:229], off
	v_pk_mul_f32 v[146:147], v[104:105], v[170:171] op_sel_hi:[1,0]
	s_nop 0
	v_pk_mul_f32 v[148:149], v[136:137], v[146:147]
	v_pk_mul_f32 v[146:147], v[134:135], v[188:189]
	global_store_dwordx4 v[186:187], v[146:149], off offset:512
	s_nop 1
	v_cvt_pk_bf16_f32 v146, v146, v147
	v_cvt_pk_bf16_f32 v147, v148, v149
	global_store_dwordx2 v[184:185], v[146:147], off offset:256
	v_pk_mul_f32 v[146:147], v[100:101], v[170:171] op_sel_hi:[1,0]
	v_pk_mul_f32 v[184:185], v[98:99], v[170:171] op_sel_hi:[1,0]
	v_pk_mul_f32 v[148:149], v[132:133], v[146:147]
	v_pk_mul_f32 v[146:147], v[130:131], v[184:185]
	global_store_dwordx4 v[186:187], v[146:149], off offset:576
.LBB0_309:
	s_and_b64 vcc, exec, s[72:73]
	s_cbranch_vccz .LBB0_311
	v_lshlrev_b64 v[146:147], 9, v[168:169]
	v_pk_mul_f32 v[148:149], v[112:113], v[170:171] op_sel_hi:[1,0]
	v_pk_mul_f32 v[168:169], v[110:111], v[170:171] op_sel_hi:[1,0]
	v_lshl_add_u64 v[172:173], s[36:37], 0, v[146:147]
	s_waitcnt vmcnt(0)
	v_pk_mul_f32 v[148:149], v[144:145], v[148:149]
	v_pk_mul_f32 v[168:169], v[142:143], v[168:169]
	v_lshl_add_u64 v[146:147], v[166:167], 1, v[172:173]
	v_cvt_pk_bf16_f32 v168, v168, v169
	v_cvt_pk_bf16_f32 v169, v148, v149
	v_mov_b32_e32 v230, v168
	v_mov_b32_e32 v231, v169
	v_pk_mul_f32 v[148:149], v[108:109], v[170:171] op_sel_hi:[1,0]
	v_pk_mul_f32 v[168:169], v[106:107], v[170:171] op_sel_hi:[1,0]
	v_pk_mul_f32 v[148:149], v[140:141], v[148:149]
	v_pk_mul_f32 v[168:169], v[138:139], v[168:169]
	s_nop 0
	v_cvt_pk_bf16_f32 v168, v168, v169
	v_cvt_pk_bf16_f32 v169, v148, v149
	v_mov_b32_e32 v232, v168
	v_mov_b32_e32 v233, v169
	s_nop 1
	v_permlane16_swap_b32_e32 v230, v232
	v_permlane16_swap_b32_e32 v231, v233
	v_lshl_add_u64 v[222:223], v[146:147], 0, v[248:249]
	global_store_dwordx4 v[222:223], v[230:233], off
	v_pk_mul_f32 v[148:149], v[104:105], v[170:171] op_sel_hi:[1,0]
	v_pk_mul_f32 v[168:169], v[102:103], v[170:171] op_sel_hi:[1,0]
	v_pk_mul_f32 v[148:149], v[136:137], v[148:149]
	v_pk_mul_f32 v[168:169], v[134:135], v[168:169]
	s_nop 0
	v_cvt_pk_bf16_f32 v168, v168, v169
	v_cvt_pk_bf16_f32 v169, v148, v149
	global_store_dwordx2 v[146:147], v[168:169], off offset:256
	v_pk_mul_f32 v[146:147], v[100:101], v[170:171] op_sel_hi:[1,0]
	v_pk_mul_f32 v[168:169], v[98:99], v[170:171] op_sel_hi:[1,0]
	v_pk_mul_f32 v[148:149], v[132:133], v[146:147]
	v_pk_mul_f32 v[146:147], v[130:131], v[168:169]
; #define PG8_LAS __attribute__((address_space(3)))
; __device__ __forceinline__ unsigned pk2(float lo, float hi) { f32x2_t v = {lo, hi}; bf16x2_t b = __builtin_convertvector(v, bf16x2_t); return __builtin_bit_cast(unsigned, b); }
;     __device__ __forceinline__ void operator()(const f32x4 (&acc)[2][2][4][2], const Unit& u, int wr, int wc, int fr, int fq) const {
;     ...
;             for (int ai = 0; ai < 2; ++ai)
; #pragma unroll
;                 for (int m = 0; m < 4; ++m) { const int rl = ai * HALF + wr * 64 + m * 16 + fr, row = u.pm * BM + rl; const f32x4 p = *(const PG8_LAS f32x4*)(P + rl * 4);
;                     const float rstd = 1.f / sqrtf(((p[0] + p[1]) + (p[2] + p[3])) * (1.f / 256.f) + EPS); const int colb = wc * 32 + 4 * fq;
;                     if (u.pn == 2) { bf16_t* op = CQN + (size_t)row * 256 + colb;
; #pragma unroll
;                         for (int bj = 0; bj < 2; ++bj)
; #pragma unroll
;                             for (int n = 0; n < 2; ++n) { const f32x4 o = (acc[ai][bj][m][n] * rstd) * gg[bj][n]; u32x2 w; w.x = pk2(o[0], o[1]); w.y = pk2(o[2], o[3]); *(u32x2*)(op + bj * HALF + n * 16) = w; }
;                     } else { bf16_t* op = LAT + (size_t)row * 256 + colb; float* fo = out + (row < NPR ? O_LATP + (size_t)row * 256 : O_LATS + (size_t)(row - NPR) * 256) + colb;
; #pragma unroll
;                         for (int bj = 0; bj < 2; ++bj)
; #pragma unroll
;                             for (int n = 0; n < 2; ++n) { const f32x4 o = (acc[ai][bj][m][n] * rstd) * gg[bj][n]; *(f32x4*)(fo + bj * HALF + n * 16) = o; u32x2 w; w.x = pk2(o[0], o[1]); w.y = pk2(o[2], o[3]); *(u32x2*)(op + bj * HALF + n * 16) = w; } } }
.LBB0_311:
	v_lshl_add_u64 v[168:169], v[166:167], 1, v[172:173]
	v_cvt_pk_bf16_f32 v146, v146, v147
	v_cvt_pk_bf16_f32 v147, v148, v149
	global_store_dwordx2 v[168:169], v[146:147], off offset:288
	v_or_b32_e32 v146, 32, v165
	v_add_u32_e32 v168, s26, v146
	v_lshl_add_u32 v146, v146, 4, 0
	v_add_u32_e32 v146, 0x20400, v146
	ds_read_b128 v[146:149], v146
	s_waitcnt lgkmcnt(0)
	v_add_f32_e32 v146, v146, v147
	v_add_f32_e32 v147, v148, v149
	v_add_f32_e32 v146, v146, v147
	v_fmamk_f32 v146, v146, 0x3b800000, v178
	v_cmp_gt_f32_e32 vcc, s97, v146
	v_mul_f32_e32 v147, 0x4f800000, v146
	s_nop 0
	v_cndmask_b32_e32 v146, v146, v147, vcc
	v_sqrt_f32_e32 v147, v146
	s_nop 0
	v_add_u32_e32 v148, -1, v147
	v_fma_f32 v149, -v148, v147, v146
	v_cmp_ge_f32_e64 s[8:9], 0, v149
	v_add_u32_e32 v149, 1, v147
	s_nop 0
	v_cndmask_b32_e64 v148, v147, v148, s[8:9]
	v_fma_f32 v147, -v149, v147, v146
	v_cmp_lt_f32_e64 s[8:9], 0, v147
	s_nop 1
	v_cndmask_b32_e64 v147, v148, v149, s[8:9]
	v_mul_f32_e32 v148, 0x37800000, v147
	v_cndmask_b32_e32 v147, v147, v148, vcc
	v_cmp_class_f32_e32 vcc, v146, v179
	s_nop 1
	v_cndmask_b32_e32 v146, v147, v146, vcc
	v_div_scale_f32 v147, s[8:9], v146, v146, 1.0
	v_rcp_f32_e32 v148, v147
	s_mov_b64 s[8:9], -1
	v_fma_f32 v149, -v147, v148, 1.0
	v_fmac_f32_e32 v148, v149, v148
	v_div_scale_f32 v149, vcc, 1.0, v146, 1.0
	v_mul_f32_e32 v154, v149, v148
	v_fma_f32 v169, -v147, v154, v149
	v_fmac_f32_e32 v154, v169, v148
	v_fma_f32 v147, -v147, v154, v149
	v_div_fmas_f32 v147, v147, v148, v154
	v_div_fixup_f32 v170, v147, v146, 1.0
	v_ashrrev_i32_e32 v169, 31, v168
	s_and_b64 vcc, exec, s[6:7]
	s_cbranch_vccnz .LBB0_317
	v_cmp_lt_i32_e32 vcc, s91, v168
	s_and_saveexec_b64 s[8:9], vcc
	s_xor_b64 s[8:9], exec, s[8:9]
	v_add_u32_e32 v154, 0xffff8000, v168
	v_lshlrev_b64 v[146:147], 8, v[154:155]
	v_lshl_add_u64 v[146:147], v[146:147], 0, s[58:59]
	s_or_saveexec_b64 s[8:9], s[8:9]
	v_lshlrev_b64 v[148:149], 8, v[168:169]
	s_xor_b64 exec, exec, s[8:9]
	v_lshl_add_u64 v[146:147], v[148:149], 0, s[60:61]
	s_or_b64 exec, exec, s[8:9]
	v_lshl_add_u64 v[146:147], v[146:147], 2, s[10:11]
	v_lshl_add_u64 v[186:187], v[166:167], 2, v[146:147]
	v_pk_mul_f32 v[146:147], v[96:97], v[170:171] op_sel_hi:[1,0]
	v_pk_mul_f32 v[188:189], v[94:95], v[170:171] op_sel_hi:[1,0]
	v_lshl_add_u64 v[172:173], v[148:149], 1, s[38:39]
	s_waitcnt vmcnt(0)
	v_pk_mul_f32 v[148:149], v[144:145], v[146:147]
	v_pk_mul_f32 v[146:147], v[142:143], v[188:189]
	v_lshl_add_u64 v[184:185], v[166:167], 1, v[172:173]
	global_store_dwordx4 v[186:187], v[146:149], off
	v_pk_mul_f32 v[188:189], v[90:91], v[170:171] op_sel_hi:[1,0]
	s_mov_b64 s[8:9], 0
	v_cvt_pk_bf16_f32 v146, v146, v147
	v_cvt_pk_bf16_f32 v147, v148, v149
	v_mov_b32_e32 v240, v146
	v_mov_b32_e32 v241, v147
	v_pk_mul_f32 v[146:147], v[92:93], v[170:171] op_sel_hi:[1,0]
	s_nop 0
	v_pk_mul_f32 v[148:149], v[140:141], v[146:147]
	v_pk_mul_f32 v[146:147], v[138:139], v[188:189]
	global_store_dwordx4 v[186:187], v[146:149], off offset:64
	v_pk_mul_f32 v[188:189], v[86:87], v[170:171] op_sel_hi:[1,0]
	s_nop 0
	v_cvt_pk_bf16_f32 v146, v146, v147
	v_cvt_pk_bf16_f32 v147, v148, v149
	v_mov_b32_e32 v242, v146
	v_mov_b32_e32 v243, v147
	s_nop 1
	v_permlane16_swap_b32_e32 v240, v242
	v_permlane16_swap_b32_e32 v241, v243
	v_lshl_add_u64 v[238:239], v[184:185], 0, v[248:249]
	global_store_dwordx4 v[238:239], v[240:243], off
	v_pk_mul_f32 v[146:147], v[88:89], v[170:171] op_sel_hi:[1,0]
	s_nop 0
	v_pk_mul_f32 v[148:149], v[136:137], v[146:147]
	v_pk_mul_f32 v[146:147], v[134:135], v[188:189]
	global_store_dwordx4 v[186:187], v[146:149], off offset:512
	s_nop 1
	v_cvt_pk_bf16_f32 v146, v146, v147
	v_cvt_pk_bf16_f32 v147, v148, v149
	global_store_dwordx2 v[184:185], v[146:147], off offset:256
	v_pk_mul_f32 v[146:147], v[84:85], v[170:171] op_sel_hi:[1,0]
	v_pk_mul_f32 v[184:185], v[82:83], v[170:171] op_sel_hi:[1,0]
	v_pk_mul_f32 v[148:149], v[132:133], v[146:147]
	v_pk_mul_f32 v[146:147], v[130:131], v[184:185]
	global_store_dwordx4 v[186:187], v[146:149], off offset:576
.LBB0_317:
	s_and_b64 vcc, exec, s[8:9]
	s_cbranch_vccz .LBB0_319
	v_lshlrev_b64 v[146:147], 9, v[168:169]
	v_pk_mul_f32 v[148:149], v[96:97], v[170:171] op_sel_hi:[1,0]
	v_pk_mul_f32 v[168:169], v[94:95], v[170:171] op_sel_hi:[1,0]
	v_lshl_add_u64 v[172:173], s[36:37], 0, v[146:147]
	s_waitcnt vmcnt(0)
	v_pk_mul_f32 v[148:149], v[144:145], v[148:149]
	v_pk_mul_f32 v[168:169], v[142:143], v[168:169]
	v_lshl_add_u64 v[146:147], v[166:167], 1, v[172:173]
	v_cvt_pk_bf16_f32 v168, v168, v169
	v_cvt_pk_bf16_f32 v169, v148, v149
	v_mov_b32_e32 v244, v168
	v_mov_b32_e32 v245, v169
	v_pk_mul_f32 v[148:149], v[92:93], v[170:171] op_sel_hi:[1,0]
	v_pk_mul_f32 v[168:169], v[90:91], v[170:171] op_sel_hi:[1,0]
	v_pk_mul_f32 v[148:149], v[140:141], v[148:149]
	v_pk_mul_f32 v[168:169], v[138:139], v[168:169]
	s_nop 0
	v_cvt_pk_bf16_f32 v168, v168, v169
	v_cvt_pk_bf16_f32 v169, v148, v149
	v_mov_b32_e32 v246, v168
	v_mov_b32_e32 v247, v169
	s_nop 1
	v_permlane16_swap_b32_e32 v244, v246
	v_permlane16_swap_b32_e32 v245, v247
	v_lshl_add_u64 v[234:235], v[146:147], 0, v[248:249]
	global_store_dwordx4 v[234:235], v[244:247], off
	v_pk_mul_f32 v[148:149], v[88:89], v[170:171] op_sel_hi:[1,0]
	v_pk_mul_f32 v[168:169], v[86:87], v[170:171] op_sel_hi:[1,0]
	v_pk_mul_f32 v[148:149], v[136:137], v[148:149]
	v_pk_mul_f32 v[168:169], v[134:135], v[168:169]
	s_nop 0
	v_cvt_pk_bf16_f32 v168, v168, v169
	v_cvt_pk_bf16_f32 v169, v148, v149
	global_store_dwordx2 v[146:147], v[168:169], off offset:256
	v_pk_mul_f32 v[146:147], v[84:85], v[170:171] op_sel_hi:[1,0]
	v_pk_mul_f32 v[168:169], v[82:83], v[170:171] op_sel_hi:[1,0]
	v_pk_mul_f32 v[148:149], v[132:133], v[146:147]
	v_pk_mul_f32 v[146:147], v[130:131], v[168:169]
; #define PG8_LAS __attribute__((address_space(3)))
; __device__ __forceinline__ unsigned pk2(float lo, float hi) { f32x2_t v = {lo, hi}; bf16x2_t b = __builtin_convertvector(v, bf16x2_t); return __builtin_bit_cast(unsigned, b); }
;     __device__ __forceinline__ void operator()(const f32x4 (&acc)[2][2][4][2], const Unit& u, int wr, int wc, int fr, int fq) const {
;     ...
;             for (int ai = 0; ai < 2; ++ai)
; #pragma unroll
;                 for (int m = 0; m < 4; ++m) { const int rl = ai * HALF + wr * 64 + m * 16 + fr, row = u.pm * BM + rl; const f32x4 p = *(const PG8_LAS f32x4*)(P + rl * 4);
;                     const float rstd = 1.f / sqrtf(((p[0] + p[1]) + (p[2] + p[3])) * (1.f / 256.f) + EPS); const int colb = wc * 32 + 4 * fq;
;                     if (u.pn == 2) { bf16_t* op = CQN + (size_t)row * 256 + colb;
; #pragma unroll
;                         for (int bj = 0; bj < 2; ++bj)
; #pragma unroll
;                             for (int n = 0; n < 2; ++n) { const f32x4 o = (acc[ai][bj][m][n] * rstd) * gg[bj][n]; u32x2 w; w.x = pk2(o[0], o[1]); w.y = pk2(o[2], o[3]); *(u32x2*)(op + bj * HALF + n * 16) = w; }
;                     } else { bf16_t* op = LAT + (size_t)row * 256 + colb; float* fo = out + (row < NPR ? O_LATP + (size_t)row * 256 : O_LATS + (size_t)(row - NPR) * 256) + colb;
; #pragma unroll
;                         for (int bj = 0; bj < 2; ++bj)
; #pragma unroll
;                             for (int n = 0; n < 2; ++n) { const f32x4 o = (acc[ai][bj][m][n] * rstd) * gg[bj][n]; *(f32x4*)(fo + bj * HALF + n * 16) = o; u32x2 w; w.x = pk2(o[0], o[1]); w.y = pk2(o[2], o[3]); *(u32x2*)(op + bj * HALF + n * 16) = w; } } }
.LBB0_319:
	v_lshl_add_u64 v[168:169], v[166:167], 1, v[172:173]
	v_cvt_pk_bf16_f32 v146, v146, v147
	v_cvt_pk_bf16_f32 v147, v148, v149
	global_store_dwordx2 v[168:169], v[146:147], off offset:288
	v_or_b32_e32 v146, 48, v165
	v_add_u32_e32 v168, s26, v146
	v_lshl_add_u32 v146, v146, 4, 0
	v_add_u32_e32 v146, 0x20400, v146
	ds_read_b128 v[146:149], v146
	s_waitcnt lgkmcnt(0)
	v_add_f32_e32 v146, v146, v147
	v_add_f32_e32 v147, v148, v149
	v_add_f32_e32 v146, v146, v147
	v_fmamk_f32 v146, v146, 0x3b800000, v178
	v_cmp_gt_f32_e32 vcc, s97, v146
	v_mul_f32_e32 v147, 0x4f800000, v146
	s_nop 0
	v_cndmask_b32_e32 v146, v146, v147, vcc
	v_sqrt_f32_e32 v147, v146
	s_nop 0
	v_add_u32_e32 v148, -1, v147
	v_fma_f32 v149, -v148, v147, v146
	v_cmp_ge_f32_e64 s[8:9], 0, v149
	v_add_u32_e32 v149, 1, v147
	s_nop 0
	v_cndmask_b32_e64 v148, v147, v148, s[8:9]
	v_fma_f32 v147, -v149, v147, v146
	v_cmp_lt_f32_e64 s[8:9], 0, v147
	s_nop 1
	v_cndmask_b32_e64 v147, v148, v149, s[8:9]
	v_mul_f32_e32 v148, 0x37800000, v147
	v_cndmask_b32_e32 v147, v147, v148, vcc
	v_cmp_class_f32_e32 vcc, v146, v179
	s_nop 1
	v_cndmask_b32_e32 v146, v147, v146, vcc
	v_div_scale_f32 v147, s[8:9], v146, v146, 1.0
	v_rcp_f32_e32 v148, v147
	s_mov_b64 s[8:9], -1
	v_fma_f32 v149, -v147, v148, 1.0
	v_fmac_f32_e32 v148, v149, v148
	v_div_scale_f32 v149, vcc, 1.0, v146, 1.0
	v_mul_f32_e32 v154, v149, v148
	v_fma_f32 v169, -v147, v154, v149
	v_fmac_f32_e32 v154, v169, v148
	v_fma_f32 v147, -v147, v154, v149
	v_div_fmas_f32 v147, v147, v148, v154
	v_div_fixup_f32 v170, v147, v146, 1.0
	v_ashrrev_i32_e32 v169, 31, v168
	s_and_b64 vcc, exec, s[6:7]
	s_cbranch_vccnz .LBB0_325
	v_cmp_lt_i32_e32 vcc, s91, v168
	s_and_saveexec_b64 s[8:9], vcc
	s_xor_b64 s[8:9], exec, s[8:9]
	v_add_u32_e32 v154, 0xffff8000, v168
	v_lshlrev_b64 v[146:147], 8, v[154:155]
	v_lshl_add_u64 v[146:147], v[146:147], 0, s[58:59]
	s_or_saveexec_b64 s[8:9], s[8:9]
	v_lshlrev_b64 v[148:149], 8, v[168:169]
	s_xor_b64 exec, exec, s[8:9]
	v_lshl_add_u64 v[146:147], v[148:149], 0, s[60:61]
	s_or_b64 exec, exec, s[8:9]
	v_lshl_add_u64 v[146:147], v[146:147], 2, s[10:11]
	v_lshl_add_u64 v[186:187], v[166:167], 2, v[146:147]
	v_pk_mul_f32 v[146:147], v[80:81], v[170:171] op_sel_hi:[1,0]
	v_pk_mul_f32 v[188:189], v[78:79], v[170:171] op_sel_hi:[1,0]
	v_lshl_add_u64 v[172:173], v[148:149], 1, s[38:39]
	s_waitcnt vmcnt(0)
	v_pk_mul_f32 v[148:149], v[144:145], v[146:147]
	v_pk_mul_f32 v[146:147], v[142:143], v[188:189]
	v_lshl_add_u64 v[184:185], v[166:167], 1, v[172:173]
	global_store_dwordx4 v[186:187], v[146:149], off
	v_pk_mul_f32 v[188:189], v[74:75], v[170:171] op_sel_hi:[1,0]
	s_mov_b64 s[8:9], 0
	v_cvt_pk_bf16_f32 v146, v146, v147
	v_cvt_pk_bf16_f32 v147, v148, v149
	v_mov_b32_e32 v226, v146
	v_mov_b32_e32 v227, v147
	v_pk_mul_f32 v[146:147], v[76:77], v[170:171] op_sel_hi:[1,0]
	s_nop 0
	v_pk_mul_f32 v[148:149], v[140:141], v[146:147]
	v_pk_mul_f32 v[146:147], v[138:139], v[188:189]
	global_store_dwordx4 v[186:187], v[146:149], off offset:64
	v_pk_mul_f32 v[188:189], v[70:71], v[170:171] op_sel_hi:[1,0]
	s_nop 0
	v_cvt_pk_bf16_f32 v146, v146, v147
	v_cvt_pk_bf16_f32 v147, v148, v149
	v_mov_b32_e32 v228, v146
	v_mov_b32_e32 v229, v147
	s_nop 1
	v_permlane16_swap_b32_e32 v226, v228
	v_permlane16_swap_b32_e32 v227, v229
	v_lshl_add_u64 v[224:225], v[184:185], 0, v[248:249]
	global_store_dwordx4 v[224:225], v[226:229], off
	v_pk_mul_f32 v[146:147], v[72:73], v[170:171] op_sel_hi:[1,0]
	s_nop 0
	v_pk_mul_f32 v[148:149], v[136:137], v[146:147]
	v_pk_mul_f32 v[146:147], v[134:135], v[188:189]
	global_store_dwordx4 v[186:187], v[146:149], off offset:512
	s_nop 1
	v_cvt_pk_bf16_f32 v146, v146, v147
	v_cvt_pk_bf16_f32 v147, v148, v149
	global_store_dwordx2 v[184:185], v[146:147], off offset:256
	v_pk_mul_f32 v[146:147], v[68:69], v[170:171] op_sel_hi:[1,0]
	v_pk_mul_f32 v[184:185], v[66:67], v[170:171] op_sel_hi:[1,0]
	v_pk_mul_f32 v[148:149], v[132:133], v[146:147]
	v_pk_mul_f32 v[146:147], v[130:131], v[184:185]
	global_store_dwordx4 v[186:187], v[146:149], off offset:576
.LBB0_325:
	s_and_b64 vcc, exec, s[8:9]
	s_cbranch_vccz .LBB0_327
	v_lshlrev_b64 v[146:147], 9, v[168:169]
	v_pk_mul_f32 v[148:149], v[80:81], v[170:171] op_sel_hi:[1,0]
	v_pk_mul_f32 v[168:169], v[78:79], v[170:171] op_sel_hi:[1,0]
	v_lshl_add_u64 v[172:173], s[36:37], 0, v[146:147]
	s_waitcnt vmcnt(0)
	v_pk_mul_f32 v[148:149], v[144:145], v[148:149]
	v_pk_mul_f32 v[168:169], v[142:143], v[168:169]
	v_lshl_add_u64 v[146:147], v[166:167], 1, v[172:173]
	v_cvt_pk_bf16_f32 v168, v168, v169
	v_cvt_pk_bf16_f32 v169, v148, v149
	v_mov_b32_e32 v230, v168
	v_mov_b32_e32 v231, v169
	v_pk_mul_f32 v[148:149], v[76:77], v[170:171] op_sel_hi:[1,0]
	v_pk_mul_f32 v[168:169], v[74:75], v[170:171] op_sel_hi:[1,0]
	v_pk_mul_f32 v[148:149], v[140:141], v[148:149]
	v_pk_mul_f32 v[168:169], v[138:139], v[168:169]
	s_nop 0
	v_cvt_pk_bf16_f32 v168, v168, v169
	v_cvt_pk_bf16_f32 v169, v148, v149
	v_mov_b32_e32 v232, v168
	v_mov_b32_e32 v233, v169
	s_nop 1
	v_permlane16_swap_b32_e32 v230, v232
	v_permlane16_swap_b32_e32 v231, v233
	v_lshl_add_u64 v[222:223], v[146:147], 0, v[248:249]
	global_store_dwordx4 v[222:223], v[230:233], off
	v_pk_mul_f32 v[148:149], v[72:73], v[170:171] op_sel_hi:[1,0]
	v_pk_mul_f32 v[168:169], v[70:71], v[170:171] op_sel_hi:[1,0]
	v_pk_mul_f32 v[148:149], v[136:137], v[148:149]
	v_pk_mul_f32 v[168:169], v[134:135], v[168:169]
	s_nop 0
	v_cvt_pk_bf16_f32 v168, v168, v169
	v_cvt_pk_bf16_f32 v169, v148, v149
	global_store_dwordx2 v[146:147], v[168:169], off offset:256
	v_pk_mul_f32 v[146:147], v[68:69], v[170:171] op_sel_hi:[1,0]
	v_pk_mul_f32 v[168:169], v[66:67], v[170:171] op_sel_hi:[1,0]
	v_pk_mul_f32 v[148:149], v[132:133], v[146:147]
	v_pk_mul_f32 v[146:147], v[130:131], v[168:169]
; #define PG8_LAS __attribute__((address_space(3)))
; __device__ __forceinline__ unsigned pk2(float lo, float hi) { f32x2_t v = {lo, hi}; bf16x2_t b = __builtin_convertvector(v, bf16x2_t); return __builtin_bit_cast(unsigned, b); }
;     __device__ __forceinline__ void operator()(const f32x4 (&acc)[2][2][4][2], const Unit& u, int wr, int wc, int fr, int fq) const {
;     ...
;             for (int ai = 0; ai < 2; ++ai)
; #pragma unroll
;                 for (int m = 0; m < 4; ++m) { const int rl = ai * HALF + wr * 64 + m * 16 + fr, row = u.pm * BM + rl; const f32x4 p = *(const PG8_LAS f32x4*)(P + rl * 4);
;                     const float rstd = 1.f / sqrtf(((p[0] + p[1]) + (p[2] + p[3])) * (1.f / 256.f) + EPS); const int colb = wc * 32 + 4 * fq;
;                     if (u.pn == 2) { bf16_t* op = CQN + (size_t)row * 256 + colb;
; #pragma unroll
;                         for (int bj = 0; bj < 2; ++bj)
; #pragma unroll
;                             for (int n = 0; n < 2; ++n) { const f32x4 o = (acc[ai][bj][m][n] * rstd) * gg[bj][n]; u32x2 w; w.x = pk2(o[0], o[1]); w.y = pk2(o[2], o[3]); *(u32x2*)(op + bj * HALF + n * 16) = w; }
;                     } else { bf16_t* op = LAT + (size_t)row * 256 + colb; float* fo = out + (row < NPR ? O_LATP + (size_t)row * 256 : O_LATS + (size_t)(row - NPR) * 256) + colb;
; #pragma unroll
;                         for (int bj = 0; bj < 2; ++bj)
; #pragma unroll
;                             for (int n = 0; n < 2; ++n) { const f32x4 o = (acc[ai][bj][m][n] * rstd) * gg[bj][n]; *(f32x4*)(fo + bj * HALF + n * 16) = o; u32x2 w; w.x = pk2(o[0], o[1]); w.y = pk2(o[2], o[3]); *(u32x2*)(op + bj * HALF + n * 16) = w; } } }
.LBB0_327:
	v_lshl_add_u64 v[168:169], v[166:167], 1, v[172:173]
	v_cvt_pk_bf16_f32 v146, v146, v147
	v_cvt_pk_bf16_f32 v147, v148, v149
	global_store_dwordx2 v[168:169], v[146:147], off offset:288
	v_add_u32_e32 v146, 0x80, v165
	v_add_u32_e32 v168, s26, v146
	v_lshl_add_u32 v146, v146, 4, 0
	v_add_u32_e32 v146, 0x20400, v146
	ds_read_b128 v[146:149], v146
	s_waitcnt lgkmcnt(0)
	v_add_f32_e32 v146, v146, v147
	v_add_f32_e32 v147, v148, v149
	v_add_f32_e32 v146, v146, v147
	v_fmamk_f32 v146, v146, 0x3b800000, v178
	v_cmp_gt_f32_e32 vcc, s97, v146
	v_mul_f32_e32 v147, 0x4f800000, v146
	s_nop 0
	v_cndmask_b32_e32 v146, v146, v147, vcc
	v_sqrt_f32_e32 v147, v146
	s_nop 0
	v_add_u32_e32 v148, -1, v147
	v_fma_f32 v149, -v148, v147, v146
	v_cmp_ge_f32_e64 s[8:9], 0, v149
	v_add_u32_e32 v149, 1, v147
	s_nop 0
	v_cndmask_b32_e64 v148, v147, v148, s[8:9]
	v_fma_f32 v147, -v149, v147, v146
	v_cmp_lt_f32_e64 s[8:9], 0, v147
	s_nop 1
	v_cndmask_b32_e64 v147, v148, v149, s[8:9]
	v_mul_f32_e32 v148, 0x37800000, v147
	v_cndmask_b32_e32 v147, v147, v148, vcc
	v_cmp_class_f32_e32 vcc, v146, v179
	s_nop 1
	v_cndmask_b32_e32 v146, v147, v146, vcc
	v_div_scale_f32 v147, s[8:9], v146, v146, 1.0
	v_rcp_f32_e32 v148, v147
	s_mov_b64 s[8:9], -1
	v_fma_f32 v149, -v147, v148, 1.0
	v_fmac_f32_e32 v148, v149, v148
	v_div_scale_f32 v149, vcc, 1.0, v146, 1.0
	v_mul_f32_e32 v154, v149, v148
	v_fma_f32 v169, -v147, v154, v149
	v_fmac_f32_e32 v154, v169, v148
	v_fma_f32 v147, -v147, v154, v149
	v_div_fmas_f32 v147, v147, v148, v154
	v_div_fixup_f32 v170, v147, v146, 1.0
	v_ashrrev_i32_e32 v169, 31, v168
	s_and_b64 vcc, exec, s[6:7]
	s_cbranch_vccnz .LBB0_333
	v_cmp_lt_i32_e32 vcc, s91, v168
	s_and_saveexec_b64 s[8:9], vcc
	s_xor_b64 s[8:9], exec, s[8:9]
	v_add_u32_e32 v154, 0xffff8000, v168
	v_lshlrev_b64 v[146:147], 8, v[154:155]
	v_lshl_add_u64 v[146:147], v[146:147], 0, s[58:59]
	s_or_saveexec_b64 s[8:9], s[8:9]
	v_lshlrev_b64 v[148:149], 8, v[168:169]
	s_xor_b64 exec, exec, s[8:9]
	v_lshl_add_u64 v[146:147], v[148:149], 0, s[60:61]
	s_or_b64 exec, exec, s[8:9]
	v_lshl_add_u64 v[146:147], v[146:147], 2, s[10:11]
	v_lshl_add_u64 v[186:187], v[166:167], 2, v[146:147]
	v_pk_mul_f32 v[146:147], v[64:65], v[170:171] op_sel_hi:[1,0]
	v_pk_mul_f32 v[188:189], v[62:63], v[170:171] op_sel_hi:[1,0]
	v_lshl_add_u64 v[172:173], v[148:149], 1, s[38:39]
	s_waitcnt vmcnt(0)
	v_pk_mul_f32 v[148:149], v[144:145], v[146:147]
	v_pk_mul_f32 v[146:147], v[142:143], v[188:189]
	v_lshl_add_u64 v[184:185], v[166:167], 1, v[172:173]
	global_store_dwordx4 v[186:187], v[146:149], off
	v_pk_mul_f32 v[188:189], v[58:59], v[170:171] op_sel_hi:[1,0]
	s_mov_b64 s[8:9], 0
	v_cvt_pk_bf16_f32 v146, v146, v147
	v_cvt_pk_bf16_f32 v147, v148, v149
	v_mov_b32_e32 v240, v146
	v_mov_b32_e32 v241, v147
	v_pk_mul_f32 v[146:147], v[60:61], v[170:171] op_sel_hi:[1,0]
	s_nop 0
	v_pk_mul_f32 v[148:149], v[140:141], v[146:147]
	v_pk_mul_f32 v[146:147], v[138:139], v[188:189]
	global_store_dwordx4 v[186:187], v[146:149], off offset:64
	v_pk_mul_f32 v[188:189], v[54:55], v[170:171] op_sel_hi:[1,0]
	s_nop 0
	v_cvt_pk_bf16_f32 v146, v146, v147
	v_cvt_pk_bf16_f32 v147, v148, v149
	v_mov_b32_e32 v242, v146
	v_mov_b32_e32 v243, v147
	s_nop 1
	v_permlane16_swap_b32_e32 v240, v242
	v_permlane16_swap_b32_e32 v241, v243
	v_lshl_add_u64 v[238:239], v[184:185], 0, v[248:249]
	global_store_dwordx4 v[238:239], v[240:243], off
	v_pk_mul_f32 v[146:147], v[56:57], v[170:171] op_sel_hi:[1,0]
	s_nop 0
	v_pk_mul_f32 v[148:149], v[136:137], v[146:147]
	v_pk_mul_f32 v[146:147], v[134:135], v[188:189]
	global_store_dwordx4 v[186:187], v[146:149], off offset:512
	s_nop 1
	v_cvt_pk_bf16_f32 v146, v146, v147
	v_cvt_pk_bf16_f32 v147, v148, v149
	global_store_dwordx2 v[184:185], v[146:147], off offset:256
	v_pk_mul_f32 v[146:147], v[52:53], v[170:171] op_sel_hi:[1,0]
	v_pk_mul_f32 v[184:185], v[50:51], v[170:171] op_sel_hi:[1,0]
	v_pk_mul_f32 v[148:149], v[132:133], v[146:147]
	v_pk_mul_f32 v[146:147], v[130:131], v[184:185]
	global_store_dwordx4 v[186:187], v[146:149], off offset:576
.LBB0_333:
	s_and_b64 vcc, exec, s[8:9]
	s_cbranch_vccz .LBB0_335
	v_lshlrev_b64 v[146:147], 9, v[168:169]
	v_pk_mul_f32 v[148:149], v[64:65], v[170:171] op_sel_hi:[1,0]
	v_pk_mul_f32 v[168:169], v[62:63], v[170:171] op_sel_hi:[1,0]
	v_lshl_add_u64 v[172:173], s[36:37], 0, v[146:147]
	s_waitcnt vmcnt(0)
	v_pk_mul_f32 v[148:149], v[144:145], v[148:149]
	v_pk_mul_f32 v[168:169], v[142:143], v[168:169]
	v_lshl_add_u64 v[146:147], v[166:167], 1, v[172:173]
	v_cvt_pk_bf16_f32 v168, v168, v169
	v_cvt_pk_bf16_f32 v169, v148, v149
	v_mov_b32_e32 v244, v168
	v_mov_b32_e32 v245, v169
	v_pk_mul_f32 v[148:149], v[60:61], v[170:171] op_sel_hi:[1,0]
	v_pk_mul_f32 v[168:169], v[58:59], v[170:171] op_sel_hi:[1,0]
	v_pk_mul_f32 v[148:149], v[140:141], v[148:149]
	v_pk_mul_f32 v[168:169], v[138:139], v[168:169]
	s_nop 0
	v_cvt_pk_bf16_f32 v168, v168, v169
	v_cvt_pk_bf16_f32 v169, v148, v149
	v_mov_b32_e32 v246, v168
	v_mov_b32_e32 v247, v169
	s_nop 1
	v_permlane16_swap_b32_e32 v244, v246
	v_permlane16_swap_b32_e32 v245, v247
	v_lshl_add_u64 v[234:235], v[146:147], 0, v[248:249]
	global_store_dwordx4 v[234:235], v[244:247], off
	v_pk_mul_f32 v[148:149], v[56:57], v[170:171] op_sel_hi:[1,0]
	v_pk_mul_f32 v[168:169], v[54:55], v[170:171] op_sel_hi:[1,0]
	v_pk_mul_f32 v[148:149], v[136:137], v[148:149]
	v_pk_mul_f32 v[168:169], v[134:135], v[168:169]
	s_nop 0
	v_cvt_pk_bf16_f32 v168, v168, v169
	v_cvt_pk_bf16_f32 v169, v148, v149
	global_store_dwordx2 v[146:147], v[168:169], off offset:256
	v_pk_mul_f32 v[146:147], v[52:53], v[170:171] op_sel_hi:[1,0]
	v_pk_mul_f32 v[168:169], v[50:51], v[170:171] op_sel_hi:[1,0]
	v_pk_mul_f32 v[148:149], v[132:133], v[146:147]
	v_pk_mul_f32 v[146:147], v[130:131], v[168:169]
; #define PG8_LAS __attribute__((address_space(3)))
; __device__ __forceinline__ unsigned pk2(float lo, float hi) { f32x2_t v = {lo, hi}; bf16x2_t b = __builtin_convertvector(v, bf16x2_t); return __builtin_bit_cast(unsigned, b); }
;     __device__ __forceinline__ void operator()(const f32x4 (&acc)[2][2][4][2], const Unit& u, int wr, int wc, int fr, int fq) const {
;     ...
;             for (int ai = 0; ai < 2; ++ai)
; #pragma unroll
;                 for (int m = 0; m < 4; ++m) { const int rl = ai * HALF + wr * 64 + m * 16 + fr, row = u.pm * BM + rl; const f32x4 p = *(const PG8_LAS f32x4*)(P + rl * 4);
;                     const float rstd = 1.f / sqrtf(((p[0] + p[1]) + (p[2] + p[3])) * (1.f / 256.f) + EPS); const int colb = wc * 32 + 4 * fq;
;                     if (u.pn == 2) { bf16_t* op = CQN + (size_t)row * 256 + colb;
; #pragma unroll
;                         for (int bj = 0; bj < 2; ++bj)
; #pragma unroll
;                             for (int n = 0; n < 2; ++n) { const f32x4 o = (acc[ai][bj][m][n] * rstd) * gg[bj][n]; u32x2 w; w.x = pk2(o[0], o[1]); w.y = pk2(o[2], o[3]); *(u32x2*)(op + bj * HALF + n * 16) = w; }
;                     } else { bf16_t* op = LAT + (size_t)row * 256 + colb; float* fo = out + (row < NPR ? O_LATP + (size_t)row * 256 : O_LATS + (size_t)(row - NPR) * 256) + colb;
; #pragma unroll
;                         for (int bj = 0; bj < 2; ++bj)
; #pragma unroll
;                             for (int n = 0; n < 2; ++n) { const f32x4 o = (acc[ai][bj][m][n] * rstd) * gg[bj][n]; *(f32x4*)(fo + bj * HALF + n * 16) = o; u32x2 w; w.x = pk2(o[0], o[1]); w.y = pk2(o[2], o[3]); *(u32x2*)(op + bj * HALF + n * 16) = w; } } }
.LBB0_335:
	v_lshl_add_u64 v[168:169], v[166:167], 1, v[172:173]
	v_cvt_pk_bf16_f32 v146, v146, v147
	v_cvt_pk_bf16_f32 v147, v148, v149
	global_store_dwordx2 v[168:169], v[146:147], off offset:288
	v_add_u32_e32 v146, 0x90, v165
	v_add_u32_e32 v168, s26, v146
	v_lshl_add_u32 v146, v146, 4, 0
	v_add_u32_e32 v146, 0x20400, v146
	ds_read_b128 v[146:149], v146
	s_waitcnt lgkmcnt(0)
	v_add_f32_e32 v146, v146, v147
	v_add_f32_e32 v147, v148, v149
	v_add_f32_e32 v146, v146, v147
	v_fmamk_f32 v146, v146, 0x3b800000, v178
	v_cmp_gt_f32_e32 vcc, s97, v146
	v_mul_f32_e32 v147, 0x4f800000, v146
	s_nop 0
	v_cndmask_b32_e32 v146, v146, v147, vcc
	v_sqrt_f32_e32 v147, v146
	s_nop 0
	v_add_u32_e32 v148, -1, v147
	v_fma_f32 v149, -v148, v147, v146
	v_cmp_ge_f32_e64 s[8:9], 0, v149
	v_add_u32_e32 v149, 1, v147
	s_nop 0
	v_cndmask_b32_e64 v148, v147, v148, s[8:9]
	v_fma_f32 v147, -v149, v147, v146
	v_cmp_lt_f32_e64 s[8:9], 0, v147
	s_nop 1
	v_cndmask_b32_e64 v147, v148, v149, s[8:9]
	v_mul_f32_e32 v148, 0x37800000, v147
	v_cndmask_b32_e32 v147, v147, v148, vcc
	v_cmp_class_f32_e32 vcc, v146, v179
	s_nop 1
	v_cndmask_b32_e32 v146, v147, v146, vcc
	v_div_scale_f32 v147, s[8:9], v146, v146, 1.0
	v_rcp_f32_e32 v148, v147
	s_mov_b64 s[8:9], -1
	v_fma_f32 v149, -v147, v148, 1.0
	v_fmac_f32_e32 v148, v149, v148
	v_div_scale_f32 v149, vcc, 1.0, v146, 1.0
	v_mul_f32_e32 v154, v149, v148
	v_fma_f32 v169, -v147, v154, v149
	v_fmac_f32_e32 v154, v169, v148
	v_fma_f32 v147, -v147, v154, v149
	v_div_fmas_f32 v147, v147, v148, v154
	v_div_fixup_f32 v170, v147, v146, 1.0
	v_ashrrev_i32_e32 v169, 31, v168
	s_and_b64 vcc, exec, s[6:7]
	s_cbranch_vccnz .LBB0_341
	v_cmp_lt_i32_e32 vcc, s91, v168
	s_and_saveexec_b64 s[8:9], vcc
	s_xor_b64 s[8:9], exec, s[8:9]
	v_add_u32_e32 v154, 0xffff8000, v168
	v_lshlrev_b64 v[146:147], 8, v[154:155]
	v_lshl_add_u64 v[146:147], v[146:147], 0, s[58:59]
	s_or_saveexec_b64 s[8:9], s[8:9]
	v_lshlrev_b64 v[148:149], 8, v[168:169]
	s_xor_b64 exec, exec, s[8:9]
	v_lshl_add_u64 v[146:147], v[148:149], 0, s[60:61]
	s_or_b64 exec, exec, s[8:9]
	v_lshl_add_u64 v[146:147], v[146:147], 2, s[10:11]
	v_lshl_add_u64 v[186:187], v[166:167], 2, v[146:147]
	v_pk_mul_f32 v[146:147], v[48:49], v[170:171] op_sel_hi:[1,0]
	v_pk_mul_f32 v[188:189], v[46:47], v[170:171] op_sel_hi:[1,0]
	v_lshl_add_u64 v[172:173], v[148:149], 1, s[38:39]
	s_waitcnt vmcnt(0)
	v_pk_mul_f32 v[148:149], v[144:145], v[146:147]
	v_pk_mul_f32 v[146:147], v[142:143], v[188:189]
	v_lshl_add_u64 v[184:185], v[166:167], 1, v[172:173]
	global_store_dwordx4 v[186:187], v[146:149], off
	v_pk_mul_f32 v[188:189], v[42:43], v[170:171] op_sel_hi:[1,0]
	s_mov_b64 s[8:9], 0
	v_cvt_pk_bf16_f32 v146, v146, v147
	v_cvt_pk_bf16_f32 v147, v148, v149
	v_mov_b32_e32 v226, v146
	v_mov_b32_e32 v227, v147
	v_pk_mul_f32 v[146:147], v[44:45], v[170:171] op_sel_hi:[1,0]
	s_nop 0
	v_pk_mul_f32 v[148:149], v[140:141], v[146:147]
	v_pk_mul_f32 v[146:147], v[138:139], v[188:189]
	global_store_dwordx4 v[186:187], v[146:149], off offset:64
	v_pk_mul_f32 v[188:189], v[38:39], v[170:171] op_sel_hi:[1,0]
	s_nop 0
	v_cvt_pk_bf16_f32 v146, v146, v147
	v_cvt_pk_bf16_f32 v147, v148, v149
	v_mov_b32_e32 v228, v146
	v_mov_b32_e32 v229, v147
	s_nop 1
	v_permlane16_swap_b32_e32 v226, v228
	v_permlane16_swap_b32_e32 v227, v229
	v_lshl_add_u64 v[224:225], v[184:185], 0, v[248:249]
	global_store_dwordx4 v[224:225], v[226:229], off
	v_pk_mul_f32 v[146:147], v[40:41], v[170:171] op_sel_hi:[1,0]
	s_nop 0
	v_pk_mul_f32 v[148:149], v[136:137], v[146:147]
	v_pk_mul_f32 v[146:147], v[134:135], v[188:189]
	global_store_dwordx4 v[186:187], v[146:149], off offset:512
	s_nop 1
	v_cvt_pk_bf16_f32 v146, v146, v147
	v_cvt_pk_bf16_f32 v147, v148, v149
	global_store_dwordx2 v[184:185], v[146:147], off offset:256
	v_pk_mul_f32 v[146:147], v[36:37], v[170:171] op_sel_hi:[1,0]
	v_pk_mul_f32 v[184:185], v[34:35], v[170:171] op_sel_hi:[1,0]
	v_pk_mul_f32 v[148:149], v[132:133], v[146:147]
	v_pk_mul_f32 v[146:147], v[130:131], v[184:185]
	global_store_dwordx4 v[186:187], v[146:149], off offset:576
.LBB0_341:
	s_and_b64 vcc, exec, s[8:9]
	s_cbranch_vccz .LBB0_343
	v_lshlrev_b64 v[146:147], 9, v[168:169]
	v_pk_mul_f32 v[148:149], v[48:49], v[170:171] op_sel_hi:[1,0]
	v_pk_mul_f32 v[168:169], v[46:47], v[170:171] op_sel_hi:[1,0]
	v_lshl_add_u64 v[172:173], s[36:37], 0, v[146:147]
	s_waitcnt vmcnt(0)
	v_pk_mul_f32 v[148:149], v[144:145], v[148:149]
	v_pk_mul_f32 v[168:169], v[142:143], v[168:169]
	v_lshl_add_u64 v[146:147], v[166:167], 1, v[172:173]
	v_cvt_pk_bf16_f32 v168, v168, v169
	v_cvt_pk_bf16_f32 v169, v148, v149
	v_mov_b32_e32 v230, v168
	v_mov_b32_e32 v231, v169
	v_pk_mul_f32 v[148:149], v[44:45], v[170:171] op_sel_hi:[1,0]
	v_pk_mul_f32 v[168:169], v[42:43], v[170:171] op_sel_hi:[1,0]
	v_pk_mul_f32 v[148:149], v[140:141], v[148:149]
	v_pk_mul_f32 v[168:169], v[138:139], v[168:169]
	s_nop 0
	v_cvt_pk_bf16_f32 v168, v168, v169
	v_cvt_pk_bf16_f32 v169, v148, v149
	v_mov_b32_e32 v232, v168
	v_mov_b32_e32 v233, v169
	s_nop 1
	v_permlane16_swap_b32_e32 v230, v232
	v_permlane16_swap_b32_e32 v231, v233
	v_lshl_add_u64 v[222:223], v[146:147], 0, v[248:249]
	global_store_dwordx4 v[222:223], v[230:233], off
	v_pk_mul_f32 v[148:149], v[40:41], v[170:171] op_sel_hi:[1,0]
	v_pk_mul_f32 v[168:169], v[38:39], v[170:171] op_sel_hi:[1,0]
	v_pk_mul_f32 v[148:149], v[136:137], v[148:149]
	v_pk_mul_f32 v[168:169], v[134:135], v[168:169]
	s_nop 0
	v_cvt_pk_bf16_f32 v168, v168, v169
	v_cvt_pk_bf16_f32 v169, v148, v149
	global_store_dwordx2 v[146:147], v[168:169], off offset:256
	v_pk_mul_f32 v[146:147], v[36:37], v[170:171] op_sel_hi:[1,0]
	v_pk_mul_f32 v[168:169], v[34:35], v[170:171] op_sel_hi:[1,0]
	v_pk_mul_f32 v[148:149], v[132:133], v[146:147]
	v_pk_mul_f32 v[146:147], v[130:131], v[168:169]
; #define PG8_LAS __attribute__((address_space(3)))
; __device__ __forceinline__ unsigned pk2(float lo, float hi) { f32x2_t v = {lo, hi}; bf16x2_t b = __builtin_convertvector(v, bf16x2_t); return __builtin_bit_cast(unsigned, b); }
;     __device__ __forceinline__ void operator()(const f32x4 (&acc)[2][2][4][2], const Unit& u, int wr, int wc, int fr, int fq) const {
;     ...
;             for (int ai = 0; ai < 2; ++ai)
; #pragma unroll
;                 for (int m = 0; m < 4; ++m) { const int rl = ai * HALF + wr * 64 + m * 16 + fr, row = u.pm * BM + rl; const f32x4 p = *(const PG8_LAS f32x4*)(P + rl * 4);
;                     const float rstd = 1.f / sqrtf(((p[0] + p[1]) + (p[2] + p[3])) * (1.f / 256.f) + EPS); const int colb = wc * 32 + 4 * fq;
;                     if (u.pn == 2) { bf16_t* op = CQN + (size_t)row * 256 + colb;
; #pragma unroll
;                         for (int bj = 0; bj < 2; ++bj)
; #pragma unroll
;                             for (int n = 0; n < 2; ++n) { const f32x4 o = (acc[ai][bj][m][n] * rstd) * gg[bj][n]; u32x2 w; w.x = pk2(o[0], o[1]); w.y = pk2(o[2], o[3]); *(u32x2*)(op + bj * HALF + n * 16) = w; }
;                     } else { bf16_t* op = LAT + (size_t)row * 256 + colb; float* fo = out + (row < NPR ? O_LATP + (size_t)row * 256 : O_LATS + (size_t)(row - NPR) * 256) + colb;
; #pragma unroll
;                         for (int bj = 0; bj < 2; ++bj)
; #pragma unroll
;                             for (int n = 0; n < 2; ++n) { const f32x4 o = (acc[ai][bj][m][n] * rstd) * gg[bj][n]; *(f32x4*)(fo + bj * HALF + n * 16) = o; u32x2 w; w.x = pk2(o[0], o[1]); w.y = pk2(o[2], o[3]); *(u32x2*)(op + bj * HALF + n * 16) = w; } } }
.LBB0_343:
	v_lshl_add_u64 v[168:169], v[166:167], 1, v[172:173]
	v_cvt_pk_bf16_f32 v146, v146, v147
	v_cvt_pk_bf16_f32 v147, v148, v149
	global_store_dwordx2 v[168:169], v[146:147], off offset:288
	v_add_u32_e32 v146, 0xa0, v165
	v_add_u32_e32 v168, s26, v146
	v_lshl_add_u32 v146, v146, 4, 0
	v_add_u32_e32 v146, 0x20400, v146
	ds_read_b128 v[146:149], v146
	s_waitcnt lgkmcnt(0)
	v_add_f32_e32 v146, v146, v147
	v_add_f32_e32 v147, v148, v149
	v_add_f32_e32 v146, v146, v147
	v_fmamk_f32 v146, v146, 0x3b800000, v178
	v_cmp_gt_f32_e32 vcc, s97, v146
	v_mul_f32_e32 v147, 0x4f800000, v146
	s_nop 0
	v_cndmask_b32_e32 v146, v146, v147, vcc
	v_sqrt_f32_e32 v147, v146
	s_nop 0
	v_add_u32_e32 v148, -1, v147
	v_fma_f32 v149, -v148, v147, v146
	v_cmp_ge_f32_e64 s[8:9], 0, v149
	v_add_u32_e32 v149, 1, v147
	s_nop 0
	v_cndmask_b32_e64 v148, v147, v148, s[8:9]
	v_fma_f32 v147, -v149, v147, v146
	v_cmp_lt_f32_e64 s[8:9], 0, v147
	s_nop 1
	v_cndmask_b32_e64 v147, v148, v149, s[8:9]
	v_mul_f32_e32 v148, 0x37800000, v147
	v_cndmask_b32_e32 v147, v147, v148, vcc
	v_cmp_class_f32_e32 vcc, v146, v179
	s_nop 1
	v_cndmask_b32_e32 v146, v147, v146, vcc
	v_div_scale_f32 v147, s[8:9], v146, v146, 1.0
	v_rcp_f32_e32 v148, v147
	s_mov_b64 s[8:9], -1
	v_fma_f32 v149, -v147, v148, 1.0
	v_fmac_f32_e32 v148, v149, v148
	v_div_scale_f32 v149, vcc, 1.0, v146, 1.0
	v_mul_f32_e32 v154, v149, v148
	v_fma_f32 v169, -v147, v154, v149
	v_fmac_f32_e32 v154, v169, v148
	v_fma_f32 v147, -v147, v154, v149
	v_div_fmas_f32 v147, v147, v148, v154
	v_div_fixup_f32 v170, v147, v146, 1.0
	v_ashrrev_i32_e32 v169, 31, v168
	s_and_b64 vcc, exec, s[6:7]
	s_cbranch_vccnz .LBB0_349
	v_cmp_lt_i32_e32 vcc, s91, v168
	s_and_saveexec_b64 s[8:9], vcc
	s_xor_b64 s[8:9], exec, s[8:9]
	v_add_u32_e32 v154, 0xffff8000, v168
	v_lshlrev_b64 v[146:147], 8, v[154:155]
	v_lshl_add_u64 v[146:147], v[146:147], 0, s[58:59]
	s_or_saveexec_b64 s[8:9], s[8:9]
	v_lshlrev_b64 v[148:149], 8, v[168:169]
	s_xor_b64 exec, exec, s[8:9]
	v_lshl_add_u64 v[146:147], v[148:149], 0, s[60:61]
	s_or_b64 exec, exec, s[8:9]
	v_lshl_add_u64 v[146:147], v[146:147], 2, s[10:11]
	v_lshl_add_u64 v[186:187], v[166:167], 2, v[146:147]
	v_pk_mul_f32 v[146:147], v[32:33], v[170:171] op_sel_hi:[1,0]
	v_pk_mul_f32 v[188:189], v[30:31], v[170:171] op_sel_hi:[1,0]
	v_lshl_add_u64 v[172:173], v[148:149], 1, s[38:39]
	s_waitcnt vmcnt(0)
	v_pk_mul_f32 v[148:149], v[144:145], v[146:147]
	v_pk_mul_f32 v[146:147], v[142:143], v[188:189]
	v_lshl_add_u64 v[184:185], v[166:167], 1, v[172:173]
	global_store_dwordx4 v[186:187], v[146:149], off
	v_pk_mul_f32 v[188:189], v[26:27], v[170:171] op_sel_hi:[1,0]
	s_mov_b64 s[8:9], 0
	v_cvt_pk_bf16_f32 v146, v146, v147
	v_cvt_pk_bf16_f32 v147, v148, v149
	v_mov_b32_e32 v240, v146
	v_mov_b32_e32 v241, v147
	v_pk_mul_f32 v[146:147], v[28:29], v[170:171] op_sel_hi:[1,0]
	s_nop 0
	v_pk_mul_f32 v[148:149], v[140:141], v[146:147]
	v_pk_mul_f32 v[146:147], v[138:139], v[188:189]
	global_store_dwordx4 v[186:187], v[146:149], off offset:64
	v_pk_mul_f32 v[188:189], v[22:23], v[170:171] op_sel_hi:[1,0]
	s_nop 0
	v_cvt_pk_bf16_f32 v146, v146, v147
	v_cvt_pk_bf16_f32 v147, v148, v149
	v_mov_b32_e32 v242, v146
	v_mov_b32_e32 v243, v147
	s_nop 1
	v_permlane16_swap_b32_e32 v240, v242
	v_permlane16_swap_b32_e32 v241, v243
	v_lshl_add_u64 v[238:239], v[184:185], 0, v[248:249]
	global_store_dwordx4 v[238:239], v[240:243], off
	v_pk_mul_f32 v[146:147], v[24:25], v[170:171] op_sel_hi:[1,0]
	s_nop 0
	v_pk_mul_f32 v[148:149], v[136:137], v[146:147]
	v_pk_mul_f32 v[146:147], v[134:135], v[188:189]
	global_store_dwordx4 v[186:187], v[146:149], off offset:512
	s_nop 1
	v_cvt_pk_bf16_f32 v146, v146, v147
	v_cvt_pk_bf16_f32 v147, v148, v149
	global_store_dwordx2 v[184:185], v[146:147], off offset:256
	v_pk_mul_f32 v[146:147], v[20:21], v[170:171] op_sel_hi:[1,0]
	v_pk_mul_f32 v[184:185], v[18:19], v[170:171] op_sel_hi:[1,0]
	v_pk_mul_f32 v[148:149], v[132:133], v[146:147]
	v_pk_mul_f32 v[146:147], v[130:131], v[184:185]
	global_store_dwordx4 v[186:187], v[146:149], off offset:576
.LBB0_349:
	s_and_b64 vcc, exec, s[8:9]
	s_cbranch_vccz .LBB0_351
	v_lshlrev_b64 v[146:147], 9, v[168:169]
	v_pk_mul_f32 v[148:149], v[32:33], v[170:171] op_sel_hi:[1,0]
	v_pk_mul_f32 v[168:169], v[30:31], v[170:171] op_sel_hi:[1,0]
	v_lshl_add_u64 v[172:173], s[36:37], 0, v[146:147]
	s_waitcnt vmcnt(0)
	v_pk_mul_f32 v[148:149], v[144:145], v[148:149]
	v_pk_mul_f32 v[168:169], v[142:143], v[168:169]
	v_lshl_add_u64 v[146:147], v[166:167], 1, v[172:173]
	v_cvt_pk_bf16_f32 v168, v168, v169
	v_cvt_pk_bf16_f32 v169, v148, v149
	v_mov_b32_e32 v244, v168
	v_mov_b32_e32 v245, v169
	v_pk_mul_f32 v[148:149], v[28:29], v[170:171] op_sel_hi:[1,0]
	v_pk_mul_f32 v[168:169], v[26:27], v[170:171] op_sel_hi:[1,0]
	v_pk_mul_f32 v[148:149], v[140:141], v[148:149]
	v_pk_mul_f32 v[168:169], v[138:139], v[168:169]
	s_nop 0
	v_cvt_pk_bf16_f32 v168, v168, v169
	v_cvt_pk_bf16_f32 v169, v148, v149
	v_mov_b32_e32 v246, v168
	v_mov_b32_e32 v247, v169
	s_nop 1
	v_permlane16_swap_b32_e32 v244, v246
	v_permlane16_swap_b32_e32 v245, v247
	v_lshl_add_u64 v[234:235], v[146:147], 0, v[248:249]
	global_store_dwordx4 v[234:235], v[244:247], off
	v_pk_mul_f32 v[148:149], v[24:25], v[170:171] op_sel_hi:[1,0]
	v_pk_mul_f32 v[168:169], v[22:23], v[170:171] op_sel_hi:[1,0]
	v_pk_mul_f32 v[148:149], v[136:137], v[148:149]
	v_pk_mul_f32 v[168:169], v[134:135], v[168:169]
	s_nop 0
	v_cvt_pk_bf16_f32 v168, v168, v169
	v_cvt_pk_bf16_f32 v169, v148, v149
	global_store_dwordx2 v[146:147], v[168:169], off offset:256
	v_pk_mul_f32 v[146:147], v[20:21], v[170:171] op_sel_hi:[1,0]
	v_pk_mul_f32 v[168:169], v[18:19], v[170:171] op_sel_hi:[1,0]
	v_pk_mul_f32 v[148:149], v[132:133], v[146:147]
	v_pk_mul_f32 v[146:147], v[130:131], v[168:169]
; #define PG8_LAS __attribute__((address_space(3)))
; __device__ __forceinline__ unsigned pk2(float lo, float hi) { f32x2_t v = {lo, hi}; bf16x2_t b = __builtin_convertvector(v, bf16x2_t); return __builtin_bit_cast(unsigned, b); }
;     __device__ __forceinline__ void operator()(const f32x4 (&acc)[2][2][4][2], const Unit& u, int wr, int wc, int fr, int fq) const {
;     ...
;             for (int ai = 0; ai < 2; ++ai)
; #pragma unroll
;                 for (int m = 0; m < 4; ++m) { const int rl = ai * HALF + wr * 64 + m * 16 + fr, row = u.pm * BM + rl; const f32x4 p = *(const PG8_LAS f32x4*)(P + rl * 4);
;                     const float rstd = 1.f / sqrtf(((p[0] + p[1]) + (p[2] + p[3])) * (1.f / 256.f) + EPS); const int colb = wc * 32 + 4 * fq;
;                     if (u.pn == 2) { bf16_t* op = CQN + (size_t)row * 256 + colb;
; #pragma unroll
;                         for (int bj = 0; bj < 2; ++bj)
; #pragma unroll
;                             for (int n = 0; n < 2; ++n) { const f32x4 o = (acc[ai][bj][m][n] * rstd) * gg[bj][n]; u32x2 w; w.x = pk2(o[0], o[1]); w.y = pk2(o[2], o[3]); *(u32x2*)(op + bj * HALF + n * 16) = w; }
;                     } else { bf16_t* op = LAT + (size_t)row * 256 + colb; float* fo = out + (row < NPR ? O_LATP + (size_t)row * 256 : O_LATS + (size_t)(row - NPR) * 256) + colb;
; #pragma unroll
;                         for (int bj = 0; bj < 2; ++bj)
; #pragma unroll
;                             for (int n = 0; n < 2; ++n) { const f32x4 o = (acc[ai][bj][m][n] * rstd) * gg[bj][n]; *(f32x4*)(fo + bj * HALF + n * 16) = o; u32x2 w; w.x = pk2(o[0], o[1]); w.y = pk2(o[2], o[3]); *(u32x2*)(op + bj * HALF + n * 16) = w; } } }
.LBB0_351:
	v_lshl_add_u64 v[168:169], v[166:167], 1, v[172:173]
	v_cvt_pk_bf16_f32 v146, v146, v147
	v_cvt_pk_bf16_f32 v147, v148, v149
	global_store_dwordx2 v[168:169], v[146:147], off offset:288
	v_add_u32_e32 v146, 0xb0, v165
	v_add_u32_e32 v168, s26, v146
	v_lshl_add_u32 v146, v146, 4, 0
	v_add_u32_e32 v146, 0x20400, v146
	ds_read_b128 v[146:149], v146
	v_ashrrev_i32_e32 v169, 31, v168
	s_waitcnt lgkmcnt(0)
	v_add_f32_e32 v146, v146, v147
	v_add_f32_e32 v147, v148, v149
	v_add_f32_e32 v146, v146, v147
	v_fmamk_f32 v146, v146, 0x3b800000, v178
	v_cmp_gt_f32_e32 vcc, s97, v146
	v_mul_f32_e32 v147, 0x4f800000, v146
	s_nop 0
	v_cndmask_b32_e32 v146, v146, v147, vcc
	v_sqrt_f32_e32 v147, v146
	s_nop 0
	v_add_u32_e32 v148, -1, v147
	v_fma_f32 v149, -v148, v147, v146
	v_cmp_ge_f32_e64 s[8:9], 0, v149
	v_add_u32_e32 v149, 1, v147
	s_nop 0
	v_cndmask_b32_e64 v148, v147, v148, s[8:9]
	v_fma_f32 v147, -v149, v147, v146
	v_cmp_lt_f32_e64 s[8:9], 0, v147
	s_nop 1
	v_cndmask_b32_e64 v147, v148, v149, s[8:9]
	v_mul_f32_e32 v148, 0x37800000, v147
	v_cndmask_b32_e32 v147, v147, v148, vcc
	v_cmp_class_f32_e32 vcc, v146, v179
	s_nop 1
	v_cndmask_b32_e32 v146, v147, v146, vcc
	v_div_scale_f32 v147, s[8:9], v146, v146, 1.0
	v_rcp_f32_e32 v148, v147
	s_mov_b64 s[8:9], -1
	v_fma_f32 v149, -v147, v148, 1.0
	v_fmac_f32_e32 v148, v149, v148
	v_div_scale_f32 v149, vcc, 1.0, v146, 1.0
	v_mul_f32_e32 v154, v149, v148
	v_fma_f32 v165, -v147, v154, v149
	v_fmac_f32_e32 v154, v165, v148
	v_fma_f32 v147, -v147, v154, v149
	v_div_fmas_f32 v147, v147, v148, v154
	v_div_fixup_f32 v170, v147, v146, 1.0
	s_and_b64 vcc, exec, s[6:7]
	s_cbranch_vccnz .LBB0_357
	v_cmp_lt_i32_e32 vcc, s91, v168
	s_and_saveexec_b64 s[6:7], vcc
	s_xor_b64 s[6:7], exec, s[6:7]
	v_add_u32_e32 v154, 0xffff8000, v168
	v_lshlrev_b64 v[146:147], 8, v[154:155]
	v_lshl_add_u64 v[146:147], v[146:147], 0, s[58:59]
	s_or_saveexec_b64 s[6:7], s[6:7]
	v_lshlrev_b64 v[148:149], 8, v[168:169]
	s_xor_b64 exec, exec, s[6:7]
	v_lshl_add_u64 v[146:147], v[148:149], 0, s[60:61]
	s_or_b64 exec, exec, s[6:7]
	v_lshl_add_u64 v[146:147], v[146:147], 2, s[10:11]
	v_lshl_add_u64 v[186:187], v[166:167], 2, v[146:147]
	v_pk_mul_f32 v[146:147], v[16:17], v[170:171] op_sel_hi:[1,0]
	v_pk_mul_f32 v[188:189], v[14:15], v[170:171] op_sel_hi:[1,0]
	v_lshl_add_u64 v[172:173], v[148:149], 1, s[38:39]
	s_waitcnt vmcnt(0)
	v_pk_mul_f32 v[148:149], v[144:145], v[146:147]
	v_pk_mul_f32 v[146:147], v[142:143], v[188:189]
	v_lshl_add_u64 v[184:185], v[166:167], 1, v[172:173]
	global_store_dwordx4 v[186:187], v[146:149], off
	v_pk_mul_f32 v[188:189], v[10:11], v[170:171] op_sel_hi:[1,0]
	s_mov_b64 s[8:9], 0
	v_cvt_pk_bf16_f32 v146, v146, v147
	v_cvt_pk_bf16_f32 v147, v148, v149
	v_mov_b32_e32 v226, v146
	v_mov_b32_e32 v227, v147
	v_pk_mul_f32 v[146:147], v[12:13], v[170:171] op_sel_hi:[1,0]
	s_nop 0
	v_pk_mul_f32 v[148:149], v[140:141], v[146:147]
	v_pk_mul_f32 v[146:147], v[138:139], v[188:189]
	global_store_dwordx4 v[186:187], v[146:149], off offset:64
	v_pk_mul_f32 v[188:189], v[6:7], v[170:171] op_sel_hi:[1,0]
	s_nop 0
	v_cvt_pk_bf16_f32 v146, v146, v147
	v_cvt_pk_bf16_f32 v147, v148, v149
	v_mov_b32_e32 v228, v146
	v_mov_b32_e32 v229, v147
	s_nop 1
	v_permlane16_swap_b32_e32 v226, v228
	v_permlane16_swap_b32_e32 v227, v229
	v_lshl_add_u64 v[224:225], v[184:185], 0, v[248:249]
	global_store_dwordx4 v[224:225], v[226:229], off
	v_pk_mul_f32 v[146:147], v[8:9], v[170:171] op_sel_hi:[1,0]
	s_nop 0
	v_pk_mul_f32 v[148:149], v[136:137], v[146:147]
	v_pk_mul_f32 v[146:147], v[134:135], v[188:189]
	global_store_dwordx4 v[186:187], v[146:149], off offset:512
	s_nop 1
	v_cvt_pk_bf16_f32 v146, v146, v147
	v_cvt_pk_bf16_f32 v147, v148, v149
	global_store_dwordx2 v[184:185], v[146:147], off offset:256
	v_pk_mul_f32 v[146:147], v[4:5], v[170:171] op_sel_hi:[1,0]
	v_pk_mul_f32 v[184:185], v[2:3], v[170:171] op_sel_hi:[1,0]
	v_pk_mul_f32 v[148:149], v[132:133], v[146:147]
	v_pk_mul_f32 v[146:147], v[130:131], v[184:185]
	global_store_dwordx4 v[186:187], v[146:149], off offset:576
.LBB0_357:
	s_and_b64 vcc, exec, s[8:9]
	s_cbranch_vccz .LBB0_359
	v_lshlrev_b64 v[146:147], 9, v[168:169]
	v_pk_mul_f32 v[148:149], v[16:17], v[170:171] op_sel_hi:[1,0]
	v_pk_mul_f32 v[168:169], v[14:15], v[170:171] op_sel_hi:[1,0]
	v_lshl_add_u64 v[172:173], s[36:37], 0, v[146:147]
	s_waitcnt vmcnt(0)
	v_pk_mul_f32 v[144:145], v[144:145], v[148:149]
	v_pk_mul_f32 v[142:143], v[142:143], v[168:169]
	v_lshl_add_u64 v[146:147], v[166:167], 1, v[172:173]
	v_cvt_pk_bf16_f32 v142, v142, v143
	v_cvt_pk_bf16_f32 v143, v144, v145
	v_mov_b32_e32 v230, v142
	v_mov_b32_e32 v231, v143
	v_pk_mul_f32 v[142:143], v[12:13], v[170:171] op_sel_hi:[1,0]
	v_pk_mul_f32 v[144:145], v[10:11], v[170:171] op_sel_hi:[1,0]
	v_pk_mul_f32 v[140:141], v[140:141], v[142:143]
	v_pk_mul_f32 v[138:139], v[138:139], v[144:145]
	s_nop 0
	v_cvt_pk_bf16_f32 v138, v138, v139
	v_cvt_pk_bf16_f32 v139, v140, v141
	v_mov_b32_e32 v232, v138
	v_mov_b32_e32 v233, v139
	s_nop 1
	v_permlane16_swap_b32_e32 v230, v232
	v_permlane16_swap_b32_e32 v231, v233
	v_lshl_add_u64 v[222:223], v[146:147], 0, v[248:249]
	global_store_dwordx4 v[222:223], v[230:233], off
	v_pk_mul_f32 v[138:139], v[8:9], v[170:171] op_sel_hi:[1,0]
	v_pk_mul_f32 v[140:141], v[6:7], v[170:171] op_sel_hi:[1,0]
	v_pk_mul_f32 v[136:137], v[136:137], v[138:139]
	v_pk_mul_f32 v[134:135], v[134:135], v[140:141]
	s_nop 0
	v_cvt_pk_bf16_f32 v134, v134, v135
	v_cvt_pk_bf16_f32 v135, v136, v137
	global_store_dwordx2 v[146:147], v[134:135], off offset:256
	v_pk_mul_f32 v[134:135], v[4:5], v[170:171] op_sel_hi:[1,0]
	v_pk_mul_f32 v[136:137], v[2:3], v[170:171] op_sel_hi:[1,0]
	v_pk_mul_f32 v[148:149], v[132:133], v[134:135]
	v_pk_mul_f32 v[146:147], v[130:131], v[136:137]
